# K-loop heads pinned to 8-byte phase 4 (three of four MFMA blocks per loop start at 4 mod 8), rstd-cache test before loads
# speedup vs baseline: 1.0025x; 1.0025x over previous
; #define PG8_STAGE(bufoff, gbase, voff) do { _Pragma("unroll") for (int _i = 0; _i < 2; ++_i) \
;         __builtin_amdgcn_global_load_lds((const unsigned*)((const char*)(gbase) + (voff)[_i]), (PG8_LAS unsigned*)(lds + (bufoff) + ldsw + _i * 8192), 16, 0, 0); } while (0)
; #define PG8_LDA(dst, b, h) do { _Pragma("unroll") for (int m = 0; m < 4; ++m) _Pragma("unroll") for (int k = 0; k < 2; ++k) dst[m][k] = *(const PG8_LAS bf16x8*)(lds + PG8_SA(b, h) + aoff + m * 2048 + k * 1024); } while (0)
; #define PG8_LDB(dst, b, h) do { _Pragma("unroll") for (int n = 0; n < 2; ++n) _Pragma("unroll") for (int k = 0; k < 2; ++k) dst[n][k] = *(const PG8_LAS bf16x8*)(lds + PG8_SB(b, h) + boff + n * 2048 + k * 1024); } while (0)
; #define PG8_MMA_NP(ai, bj, At, Bt) do { _Pragma("unroll") for (int m = 0; m < 4; ++m) _Pragma("unroll") for (int n = 0; n < 2; ++n) _Pragma("unroll") for (int k = 0; k < 2; ++k) \
;         acc[ai][bj][m][n] = __builtin_amdgcn_mfma_f32_16x16x32_bf16(Bt[n][k], At[m][k], acc[ai][bj][m][n], 0, 0, 0); } while (0)
; template <class Epi, class Sched, bool ALIGN_EPI = false, bool SP2 = false>
; __device__ __forceinline__ void gemm_phase(PG8_LAS unsigned char* lds, const Gemm g, const Sched& S, const Epi& E) {
;     ...
;         const bool has_next = S.next(ui + 1, nxt);
;         const char* nA = has_next ? (const char*)g.A + (size_t)nxt.pm * tstep : cA; const char* nB = has_next ? (const char*)g.Bt + (size_t)nxt.pn * tstep : cB;
;         for (int t = 0; t < nt; t += 2) {
;             const bool last = (t == nt - 2);
;             const char* a1 = cA + (size_t)(t + 1) * kstep;
;             const char* a2 = last ? nA : cA + (size_t)(t + 2) * kstep; const char* b2 = last ? nB : cB + (size_t)(t + 2) * kstep;
;             const char* a3 = a2 + kstep; const char* b3 = b2 + kstep;
;             if (last && has_next) S.a_ready(nxt);
;             if constexpr (SP2) {
;             PG8_LDB(B0, 0, 0); PG8_LDB(B1, 0, 1); PG8_SCHED; PG8_LDA(At, 0, 0); PG8_STAGE(PG8_SA(1, 1), a1 + hstep, voffA);
;             PG8_WAIT_V(8); PG8_WAIT_L(0); PG8_BAR; __builtin_amdgcn_s_setprio(1); PG8_MMA_NP(0, 0, At, B0); PG8_MMA_NP(0, 1, At, B1); __builtin_amdgcn_s_setprio(0); PG8_BAR; PG8_SCHED;
;             PG8_LDA(At, 0, 1); PG8_STAGE(PG8_SB(0, 0), b2, voffB); PG8_STAGE(PG8_SB(0, 1), b2 + hstep, voffB); PG8_STAGE(PG8_SA(0, 0), a2, voffA);
.LBB0_165:
	s_ashr_i32 s47, s46, 31
	s_lshl_b64 s[14:15], s[46:47], 19
	s_add_u32 s50, s86, s14
	s_addc_u32 s51, s87, s15
	s_and_b64 s[14:15], s[40:41], exec
	s_cselect_b32 s47, s51, s3
	s_cselect_b32 s59, s50, s2
	s_ashr_i32 s45, s44, 31
	s_lshl_b64 s[14:15], s[44:45], 19
	v_readlane_b32 s22, v244, 18
	s_add_u32 s52, s22, s14
	v_readlane_b32 s14, v244, 19
	s_addc_u32 s53, s14, s15
	s_and_b64 s[14:15], s[40:41], exec
	s_cselect_b32 s45, s53, s13
	s_cselect_b32 s60, s52, s12
	s_add_u32 s2, s2, 0x40080
	s_addc_u32 s3, s3, 0
	s_add_u32 s61, s12, 0x100
	s_addc_u32 s62, s13, 0
	s_mov_b32 s63, -2
	s_add_u32 s12, s2, 0xfffc0080
	s_addc_u32 s13, s3, -1
	s_add_i32 s22, 0, 0x10000
	s_cmp_eq_u32 s63, 12
	s_cselect_b32 s15, s47, s13
	s_cselect_b32 s14, s59, s12
	s_cselect_b32 s13, s45, s62
	s_cselect_b32 s12, s60, s61
	s_add_i32 s23, 0, 0x14000
	v_add_u32_e32 v154, s22, v183
	v_add_u32_e32 v162, s23, v183
	ds_read_b128 v[130:133], v154
	ds_read_b128 v[146:149], v154 offset:1024
	ds_read_b128 v[150:153], v154 offset:2048
	ds_read_b128 v[154:157], v154 offset:3072
	ds_read_b128 v[158:161], v162
	ds_read_b128 v[178:181], v162 offset:1024
	ds_read_b128 v[186:189], v162 offset:2048
	ds_read_b128 v[202:205], v162 offset:3072
	v_lshl_add_u64 v[162:163], s[2:3], 0, v[142:143]
	s_add_i32 m0, s10, 0xc000
	ds_read_b128 v[206:209], v185
	ds_read_b128 v[210:213], v185 offset:1024
	ds_read_b128 v[214:217], v185 offset:2048
	ds_read_b128 v[218:221], v185 offset:3072
	ds_read_b128 v[222:225], v185 offset:4096
	ds_read_b128 v[226:229], v185 offset:5120
	ds_read_b128 v[230:233], v185 offset:6144
	ds_read_b128 v[234:237], v185 offset:7168
	global_load_lds_dwordx4 v[162:163], off
	v_lshl_add_u64 v[162:163], s[2:3], 0, v[144:145]
	s_add_i32 m0, s10, 0xe000
	s_nop 0
	global_load_lds_dwordx4 v[162:163], off
	s_waitcnt vmcnt(8)
	s_waitcnt lgkmcnt(0)
	s_barrier
	s_setprio 1
	s_waitcnt lgkmcnt(0)
	v_mfma_f32_16x16x32_bf16 v[126:129], v[130:133], v[206:209], 0
	v_mfma_f32_16x16x32_bf16 v[118:121], v[150:153], v[206:209], 0
	v_mfma_f32_16x16x32_bf16 v[110:113], v[130:133], v[214:217], 0
	v_mfma_f32_16x16x32_bf16 v[102:105], v[150:153], v[214:217], 0
	v_mfma_f32_16x16x32_bf16 v[94:97], v[130:133], v[222:225], 0
	v_mfma_f32_16x16x32_bf16 v[86:89], v[150:153], v[222:225], 0
	v_mfma_f32_16x16x32_bf16 v[78:81], v[130:133], v[230:233], 0
	v_mfma_f32_16x16x32_bf16 v[70:73], v[150:153], v[230:233], 0
	v_mfma_f32_16x16x32_bf16 v[122:125], v[158:161], v[206:209], 0
	v_mfma_f32_16x16x32_bf16 v[114:117], v[186:189], v[206:209], 0
	v_mfma_f32_16x16x32_bf16 v[106:109], v[158:161], v[214:217], 0
	v_mfma_f32_16x16x32_bf16 v[98:101], v[186:189], v[214:217], 0
	v_mfma_f32_16x16x32_bf16 v[90:93], v[158:161], v[222:225], 0
	v_mfma_f32_16x16x32_bf16 v[82:85], v[186:189], v[222:225], 0
	v_mfma_f32_16x16x32_bf16 v[74:77], v[158:161], v[230:233], 0
	v_mfma_f32_16x16x32_bf16 v[66:69], v[186:189], v[230:233], 0
	v_mfma_f32_16x16x32_bf16 v[126:129], v[146:149], v[210:213], v[126:129]
	v_mfma_f32_16x16x32_bf16 v[118:121], v[154:157], v[210:213], v[118:121]
	v_mfma_f32_16x16x32_bf16 v[110:113], v[146:149], v[218:221], v[110:113]
	v_mfma_f32_16x16x32_bf16 v[102:105], v[154:157], v[218:221], v[102:105]
	v_mfma_f32_16x16x32_bf16 v[94:97], v[146:149], v[226:229], v[94:97]
	v_mfma_f32_16x16x32_bf16 v[86:89], v[154:157], v[226:229], v[86:89]
	v_mfma_f32_16x16x32_bf16 v[78:81], v[146:149], v[234:237], v[78:81]
	v_mfma_f32_16x16x32_bf16 v[70:73], v[154:157], v[234:237], v[70:73]
	v_mfma_f32_16x16x32_bf16 v[122:125], v[178:181], v[210:213], v[122:125]
	v_mfma_f32_16x16x32_bf16 v[114:117], v[202:205], v[210:213], v[114:117]
	v_mfma_f32_16x16x32_bf16 v[106:109], v[178:181], v[218:221], v[106:109]
	v_mfma_f32_16x16x32_bf16 v[98:101], v[202:205], v[218:221], v[98:101]
	v_mfma_f32_16x16x32_bf16 v[90:93], v[178:181], v[226:229], v[90:93]
	v_mfma_f32_16x16x32_bf16 v[82:85], v[202:205], v[226:229], v[82:85]
	v_mfma_f32_16x16x32_bf16 v[74:77], v[178:181], v[234:237], v[74:77]
	v_mfma_f32_16x16x32_bf16 v[66:69], v[202:205], v[234:237], v[66:69]
	s_setprio 0
	s_barrier
	s_add_i32 s22, s22, s8
	v_lshl_add_u64 v[162:163], s[12:13], 0, v[0:1]
	s_mov_b32 m0, s22
	ds_read_b128 v[206:209], v185 offset:16384
	ds_read_b128 v[210:213], v185 offset:17408
	ds_read_b128 v[214:217], v185 offset:18432
	ds_read_b128 v[218:221], v185 offset:19456
	ds_read_b128 v[222:225], v185 offset:20480
	ds_read_b128 v[226:229], v185 offset:21504
	ds_read_b128 v[230:233], v185 offset:22528
	ds_read_b128 v[234:237], v185 offset:23552
	global_load_lds_dwordx4 v[162:163], off
	s_add_i32 m0, s22, 0x2000
	s_add_u32 s64, s12, 0x40000
	v_lshl_add_u64 v[190:191], s[12:13], 0, v[134:135]
	s_addc_u32 s65, s13, 0
	s_add_i32 s22, s23, s8
	global_load_lds_dwordx4 v[190:191], off
	v_lshl_add_u64 v[238:239], s[64:65], 0, v[0:1]
	s_mov_b32 m0, s22
	v_lshl_add_u64 v[240:241], s[14:15], 0, v[136:137]
	global_load_lds_dwordx4 v[238:239], off
	v_lshl_add_u64 v[238:239], s[64:65], 0, v[134:135]
	s_add_i32 m0, s22, 0x2000
	s_nop 0
	global_load_lds_dwordx4 v[238:239], off
	v_lshl_add_u64 v[238:239], s[14:15], 0, v[138:139]
	s_mov_b32 m0, s10
	s_nop 0
	global_load_lds_dwordx4 v[238:239], off
	s_mov_b32 m0, s29
	s_nop 0
	global_load_lds_dwordx4 v[240:241], off
	s_waitcnt vmcnt(8)
	s_waitcnt lgkmcnt(0)
	s_barrier
; #define PG8_STAGE(bufoff, gbase, voff) do { _Pragma("unroll") for (int _i = 0; _i < 2; ++_i) \
;         __builtin_amdgcn_global_load_lds((const unsigned*)((const char*)(gbase) + (voff)[_i]), (PG8_LAS unsigned*)(lds + (bufoff) + ldsw + _i * 8192), 16, 0, 0); } while (0)
; #define PG8_LDA(dst, b, h) do { _Pragma("unroll") for (int m = 0; m < 4; ++m) _Pragma("unroll") for (int k = 0; k < 2; ++k) dst[m][k] = *(const PG8_LAS bf16x8*)(lds + PG8_SA(b, h) + aoff + m * 2048 + k * 1024); } while (0)
; #define PG8_LDB(dst, b, h) do { _Pragma("unroll") for (int n = 0; n < 2; ++n) _Pragma("unroll") for (int k = 0; k < 2; ++k) dst[n][k] = *(const PG8_LAS bf16x8*)(lds + PG8_SB(b, h) + boff + n * 2048 + k * 1024); } while (0)
; #define PG8_MMA_NP(ai, bj, At, Bt) do { _Pragma("unroll") for (int m = 0; m < 4; ++m) _Pragma("unroll") for (int n = 0; n < 2; ++n) _Pragma("unroll") for (int k = 0; k < 2; ++k) \
;         acc[ai][bj][m][n] = __builtin_amdgcn_mfma_f32_16x16x32_bf16(Bt[n][k], At[m][k], acc[ai][bj][m][n], 0, 0, 0); } while (0)
; #define PG8_WAIT_V(n) asm volatile("s_waitcnt vmcnt(" #n ")" ::: "memory")
; #define PG8_WAIT_L(n) asm volatile("s_waitcnt lgkmcnt(" #n ")" ::: "memory")
; #define PG8_BAR __builtin_amdgcn_s_barrier()
; #define PG8_SCHED __builtin_amdgcn_sched_barrier(0)
; template <class Epi, class Sched, bool ALIGN_EPI = false, bool SP2 = false>
; __device__ __forceinline__ void gemm_phase(PG8_LAS unsigned char* lds, const Gemm g, const Sched& S, const Epi& E) {
;     ...
;             PG8_WAIT_V(8); PG8_WAIT_L(0); PG8_BAR; __builtin_amdgcn_s_setprio(1); PG8_MMA_NP(1, 0, At, B0); PG8_MMA_NP(1, 1, At, B1); __builtin_amdgcn_s_setprio(0); PG8_BAR; PG8_SCHED;
;             PG8_LDB(B0, 1, 0); PG8_LDB(B1, 1, 1); PG8_SCHED; PG8_LDA(At, 1, 0); PG8_STAGE(PG8_SA(0, 1), a2 + hstep, voffA);
;             PG8_WAIT_V(8); PG8_WAIT_L(0); PG8_BAR; __builtin_amdgcn_s_setprio(1); PG8_MMA_NP(0, 0, At, B0); PG8_MMA_NP(0, 1, At, B1); __builtin_amdgcn_s_setprio(0); PG8_BAR; PG8_SCHED;
	s_setprio 1
	s_waitcnt lgkmcnt(0)
	v_mfma_f32_16x16x32_bf16 v[62:65], v[130:133], v[206:209], 0
	v_mfma_f32_16x16x32_bf16 v[54:57], v[150:153], v[206:209], 0
	v_mfma_f32_16x16x32_bf16 v[46:49], v[130:133], v[214:217], 0
	v_mfma_f32_16x16x32_bf16 v[38:41], v[150:153], v[214:217], 0
	v_mfma_f32_16x16x32_bf16 v[30:33], v[130:133], v[222:225], 0
	v_mfma_f32_16x16x32_bf16 v[22:25], v[150:153], v[222:225], 0
	v_mfma_f32_16x16x32_bf16 v[14:17], v[130:133], v[230:233], 0
	v_mfma_f32_16x16x32_bf16 v[6:9], v[150:153], v[230:233], 0
	v_mfma_f32_16x16x32_bf16 v[58:61], v[158:161], v[206:209], 0
	v_mfma_f32_16x16x32_bf16 v[50:53], v[186:189], v[206:209], 0
	v_mfma_f32_16x16x32_bf16 v[42:45], v[158:161], v[214:217], 0
	v_mfma_f32_16x16x32_bf16 v[34:37], v[186:189], v[214:217], 0
	v_mfma_f32_16x16x32_bf16 v[26:29], v[158:161], v[222:225], 0
	v_mfma_f32_16x16x32_bf16 v[18:21], v[186:189], v[222:225], 0
	v_mfma_f32_16x16x32_bf16 v[10:13], v[158:161], v[230:233], 0
	v_mfma_f32_16x16x32_bf16 v[2:5], v[186:189], v[230:233], 0
	v_mfma_f32_16x16x32_bf16 v[62:65], v[146:149], v[210:213], v[62:65]
	v_mfma_f32_16x16x32_bf16 v[54:57], v[154:157], v[210:213], v[54:57]
	v_mfma_f32_16x16x32_bf16 v[46:49], v[146:149], v[218:221], v[46:49]
	v_mfma_f32_16x16x32_bf16 v[38:41], v[154:157], v[218:221], v[38:41]
	v_mfma_f32_16x16x32_bf16 v[30:33], v[146:149], v[226:229], v[30:33]
	v_mfma_f32_16x16x32_bf16 v[22:25], v[154:157], v[226:229], v[22:25]
	v_mfma_f32_16x16x32_bf16 v[14:17], v[146:149], v[234:237], v[14:17]
	v_mfma_f32_16x16x32_bf16 v[6:9], v[154:157], v[234:237], v[6:9]
	v_mfma_f32_16x16x32_bf16 v[58:61], v[178:181], v[210:213], v[58:61]
	v_mfma_f32_16x16x32_bf16 v[50:53], v[202:205], v[210:213], v[50:53]
	v_mfma_f32_16x16x32_bf16 v[42:45], v[178:181], v[218:221], v[42:45]
	v_mfma_f32_16x16x32_bf16 v[34:37], v[202:205], v[218:221], v[34:37]
	v_mfma_f32_16x16x32_bf16 v[26:29], v[178:181], v[226:229], v[26:29]
	v_mfma_f32_16x16x32_bf16 v[18:21], v[202:205], v[226:229], v[18:21]
	v_mfma_f32_16x16x32_bf16 v[10:13], v[178:181], v[234:237], v[10:13]
	v_mfma_f32_16x16x32_bf16 v[2:5], v[202:205], v[234:237], v[2:5]
	s_setprio 0
	s_barrier
	s_add_i32 s22, 0, 0x18000
	s_add_i32 s23, 0, 0x1c000
	v_add_u32_e32 v154, s22, v183
	v_add_u32_e32 v202, s23, v183
	ds_read_b128 v[130:133], v154
	ds_read_b128 v[146:149], v154 offset:1024
	ds_read_b128 v[150:153], v154 offset:2048
	ds_read_b128 v[154:157], v154 offset:3072
	ds_read_b128 v[158:161], v202
	ds_read_b128 v[178:181], v202 offset:1024
	ds_read_b128 v[186:189], v202 offset:2048
	ds_read_b128 v[202:205], v202 offset:3072
	s_add_u32 s14, s14, 0x40000
	s_addc_u32 s15, s15, 0
	s_mov_b32 m0, s30
	v_lshl_add_u64 v[242:243], s[14:15], 0, v[138:139]
	ds_read_b128 v[206:209], v185 offset:32768
	ds_read_b128 v[210:213], v185 offset:33792
	ds_read_b128 v[214:217], v185 offset:34816
	ds_read_b128 v[218:221], v185 offset:35840
	ds_read_b128 v[222:225], v185 offset:36864
	ds_read_b128 v[226:229], v185 offset:37888
	ds_read_b128 v[230:233], v185 offset:38912
	ds_read_b128 v[234:237], v185 offset:39936
	global_load_lds_dwordx4 v[242:243], off
	v_lshl_add_u64 v[242:243], s[14:15], 0, v[136:137]
	s_mov_b32 m0, s31
	s_nop 0
	global_load_lds_dwordx4 v[242:243], off
	s_waitcnt vmcnt(8)
	s_waitcnt lgkmcnt(0)
	s_barrier
	s_setprio 1
	s_waitcnt lgkmcnt(0)
	v_mfma_f32_16x16x32_bf16 v[126:129], v[130:133], v[206:209], v[126:129]
	v_mfma_f32_16x16x32_bf16 v[118:121], v[150:153], v[206:209], v[118:121]
	v_mfma_f32_16x16x32_bf16 v[110:113], v[130:133], v[214:217], v[110:113]
	v_mfma_f32_16x16x32_bf16 v[102:105], v[150:153], v[214:217], v[102:105]
	v_mfma_f32_16x16x32_bf16 v[94:97], v[130:133], v[222:225], v[94:97]
	v_mfma_f32_16x16x32_bf16 v[86:89], v[150:153], v[222:225], v[86:89]
	v_mfma_f32_16x16x32_bf16 v[78:81], v[130:133], v[230:233], v[78:81]
	v_mfma_f32_16x16x32_bf16 v[70:73], v[150:153], v[230:233], v[70:73]
	v_mfma_f32_16x16x32_bf16 v[122:125], v[158:161], v[206:209], v[122:125]
	v_mfma_f32_16x16x32_bf16 v[114:117], v[186:189], v[206:209], v[114:117]
	v_mfma_f32_16x16x32_bf16 v[106:109], v[158:161], v[214:217], v[106:109]
	v_mfma_f32_16x16x32_bf16 v[98:101], v[186:189], v[214:217], v[98:101]
	v_mfma_f32_16x16x32_bf16 v[90:93], v[158:161], v[222:225], v[90:93]
	v_mfma_f32_16x16x32_bf16 v[82:85], v[186:189], v[222:225], v[82:85]
	v_mfma_f32_16x16x32_bf16 v[74:77], v[158:161], v[230:233], v[74:77]
	v_mfma_f32_16x16x32_bf16 v[66:69], v[186:189], v[230:233], v[66:69]
	v_mfma_f32_16x16x32_bf16 v[126:129], v[146:149], v[210:213], v[126:129]
	v_mfma_f32_16x16x32_bf16 v[118:121], v[154:157], v[210:213], v[118:121]
	v_mfma_f32_16x16x32_bf16 v[110:113], v[146:149], v[218:221], v[110:113]
	v_mfma_f32_16x16x32_bf16 v[102:105], v[154:157], v[218:221], v[102:105]
	v_mfma_f32_16x16x32_bf16 v[94:97], v[146:149], v[226:229], v[94:97]
	v_mfma_f32_16x16x32_bf16 v[86:89], v[154:157], v[226:229], v[86:89]
	v_mfma_f32_16x16x32_bf16 v[78:81], v[146:149], v[234:237], v[78:81]
	v_mfma_f32_16x16x32_bf16 v[70:73], v[154:157], v[234:237], v[70:73]
	v_mfma_f32_16x16x32_bf16 v[122:125], v[178:181], v[210:213], v[122:125]
	v_mfma_f32_16x16x32_bf16 v[114:117], v[202:205], v[210:213], v[114:117]
	v_mfma_f32_16x16x32_bf16 v[106:109], v[178:181], v[218:221], v[106:109]
	v_mfma_f32_16x16x32_bf16 v[98:101], v[202:205], v[218:221], v[98:101]
	v_mfma_f32_16x16x32_bf16 v[90:93], v[178:181], v[226:229], v[90:93]
	v_mfma_f32_16x16x32_bf16 v[82:85], v[202:205], v[226:229], v[82:85]
	v_mfma_f32_16x16x32_bf16 v[74:77], v[178:181], v[234:237], v[74:77]
	v_mfma_f32_16x16x32_bf16 v[66:69], v[202:205], v[234:237], v[66:69]
	s_setprio 0
	s_barrier
; #define PG8_STAGE(bufoff, gbase, voff) do { _Pragma("unroll") for (int _i = 0; _i < 2; ++_i) \
;         __builtin_amdgcn_global_load_lds((const unsigned*)((const char*)(gbase) + (voff)[_i]), (PG8_LAS unsigned*)(lds + (bufoff) + ldsw + _i * 8192), 16, 0, 0); } while (0)
; #define PG8_LDA(dst, b, h) do { _Pragma("unroll") for (int m = 0; m < 4; ++m) _Pragma("unroll") for (int k = 0; k < 2; ++k) dst[m][k] = *(const PG8_LAS bf16x8*)(lds + PG8_SA(b, h) + aoff + m * 2048 + k * 1024); } while (0)
; #define PG8_MMA_NP(ai, bj, At, Bt) do { _Pragma("unroll") for (int m = 0; m < 4; ++m) _Pragma("unroll") for (int n = 0; n < 2; ++n) _Pragma("unroll") for (int k = 0; k < 2; ++k) \
;         acc[ai][bj][m][n] = __builtin_amdgcn_mfma_f32_16x16x32_bf16(Bt[n][k], At[m][k], acc[ai][bj][m][n], 0, 0, 0); } while (0)
; #define PG8_WAIT_V(n) asm volatile("s_waitcnt vmcnt(" #n ")" ::: "memory")
; #define PG8_WAIT_L(n) asm volatile("s_waitcnt lgkmcnt(" #n ")" ::: "memory")
; #define PG8_BAR __builtin_amdgcn_s_barrier()
; #define PG8_SCHED __builtin_amdgcn_sched_barrier(0)
; template <class Epi, class Sched, bool ALIGN_EPI = false, bool SP2 = false>
; __device__ __forceinline__ void gemm_phase(PG8_LAS unsigned char* lds, const Gemm g, const Sched& S, const Epi& E) {
;     ...
;         for (int t = 0; t < nt; t += 2) {
;     ...
;             PG8_LDA(At, 1, 1); PG8_STAGE(PG8_SB(1, 0), b3, voffB); PG8_STAGE(PG8_SB(1, 1), b3 + hstep, voffB); PG8_STAGE(PG8_SA(1, 0), a3, voffA);
;             PG8_WAIT_V(8); PG8_WAIT_L(0); PG8_BAR; __builtin_amdgcn_s_setprio(1); PG8_MMA_NP(1, 0, At, B0); PG8_MMA_NP(1, 1, At, B1); __builtin_amdgcn_s_setprio(0); PG8_BAR; PG8_SCHED;
	s_add_i32 s14, s22, s8
	v_lshl_add_u64 v[162:163], v[162:163], 0, s[20:21]
	s_mov_b32 m0, s14
	ds_read_b128 v[206:209], v185 offset:49152
	ds_read_b128 v[210:213], v185 offset:50176
	ds_read_b128 v[214:217], v185 offset:51200
	ds_read_b128 v[218:221], v185 offset:52224
	ds_read_b128 v[222:225], v185 offset:53248
	ds_read_b128 v[226:229], v185 offset:54272
	ds_read_b128 v[230:233], v185 offset:55296
	ds_read_b128 v[234:237], v185 offset:56320
	global_load_lds_dwordx4 v[162:163], off
	s_add_i32 m0, s14, 0x2000
	s_add_u32 s12, s12, 0x40080
	v_lshl_add_u64 v[162:163], v[190:191], 0, s[20:21]
	s_addc_u32 s13, s13, 0
	s_add_i32 s14, s23, s8
	global_load_lds_dwordx4 v[162:163], off
	v_lshl_add_u64 v[162:163], s[12:13], 0, v[0:1]
	s_mov_b32 m0, s14
	s_nop 0
	global_load_lds_dwordx4 v[162:163], off
	v_lshl_add_u64 v[162:163], s[12:13], 0, v[134:135]
	s_add_i32 m0, s14, 0x2000
	s_nop 0
	global_load_lds_dwordx4 v[162:163], off
	v_lshl_add_u64 v[162:163], v[238:239], 0, s[20:21]
	s_mov_b32 m0, s54
	s_nop 0
	global_load_lds_dwordx4 v[162:163], off
	v_lshl_add_u64 v[162:163], v[240:241], 0, s[20:21]
	s_mov_b32 m0, s55
	s_nop 0
	global_load_lds_dwordx4 v[162:163], off
	s_waitcnt vmcnt(8)
	s_waitcnt lgkmcnt(0)
	s_barrier
	s_setprio 1
	s_waitcnt lgkmcnt(0)
	v_mfma_f32_16x16x32_bf16 v[62:65], v[130:133], v[206:209], v[62:65]
	v_mfma_f32_16x16x32_bf16 v[54:57], v[150:153], v[206:209], v[54:57]
	v_mfma_f32_16x16x32_bf16 v[46:49], v[130:133], v[214:217], v[46:49]
	v_mfma_f32_16x16x32_bf16 v[38:41], v[150:153], v[214:217], v[38:41]
	v_mfma_f32_16x16x32_bf16 v[30:33], v[130:133], v[222:225], v[30:33]
	v_mfma_f32_16x16x32_bf16 v[22:25], v[150:153], v[222:225], v[22:25]
	v_mfma_f32_16x16x32_bf16 v[14:17], v[130:133], v[230:233], v[14:17]
	v_mfma_f32_16x16x32_bf16 v[6:9], v[150:153], v[230:233], v[6:9]
	v_mfma_f32_16x16x32_bf16 v[58:61], v[158:161], v[206:209], v[58:61]
	v_mfma_f32_16x16x32_bf16 v[50:53], v[186:189], v[206:209], v[50:53]
	v_mfma_f32_16x16x32_bf16 v[42:45], v[158:161], v[214:217], v[42:45]
	v_mfma_f32_16x16x32_bf16 v[34:37], v[186:189], v[214:217], v[34:37]
	v_mfma_f32_16x16x32_bf16 v[26:29], v[158:161], v[222:225], v[26:29]
	v_mfma_f32_16x16x32_bf16 v[18:21], v[186:189], v[222:225], v[18:21]
	v_mfma_f32_16x16x32_bf16 v[10:13], v[158:161], v[230:233], v[10:13]
	v_mfma_f32_16x16x32_bf16 v[2:5], v[186:189], v[230:233], v[2:5]
	v_mfma_f32_16x16x32_bf16 v[62:65], v[146:149], v[210:213], v[62:65]
	v_mfma_f32_16x16x32_bf16 v[54:57], v[154:157], v[210:213], v[54:57]
	v_mfma_f32_16x16x32_bf16 v[46:49], v[146:149], v[218:221], v[46:49]
	v_mfma_f32_16x16x32_bf16 v[38:41], v[154:157], v[218:221], v[38:41]
	v_mfma_f32_16x16x32_bf16 v[30:33], v[146:149], v[226:229], v[30:33]
	v_mfma_f32_16x16x32_bf16 v[22:25], v[154:157], v[226:229], v[22:25]
	v_mfma_f32_16x16x32_bf16 v[14:17], v[146:149], v[234:237], v[14:17]
	v_mfma_f32_16x16x32_bf16 v[6:9], v[154:157], v[234:237], v[6:9]
	v_mfma_f32_16x16x32_bf16 v[58:61], v[178:181], v[210:213], v[58:61]
	v_mfma_f32_16x16x32_bf16 v[50:53], v[202:205], v[210:213], v[50:53]
	v_mfma_f32_16x16x32_bf16 v[42:45], v[178:181], v[218:221], v[42:45]
	v_mfma_f32_16x16x32_bf16 v[34:37], v[202:205], v[218:221], v[34:37]
	v_mfma_f32_16x16x32_bf16 v[26:29], v[178:181], v[226:229], v[26:29]
	v_mfma_f32_16x16x32_bf16 v[18:21], v[202:205], v[226:229], v[18:21]
	v_mfma_f32_16x16x32_bf16 v[10:13], v[178:181], v[234:237], v[10:13]
	v_mfma_f32_16x16x32_bf16 v[2:5], v[202:205], v[234:237], v[2:5]
	s_setprio 0
	s_barrier
	s_add_i32 s63, s63, 2
	s_add_u32 s2, s2, 0x100
	s_addc_u32 s3, s3, 0
	s_add_u32 s61, s61, 0x100
	s_addc_u32 s62, s62, 0
	s_cmp_gt_u32 s63, 13
	s_cbranch_scc0 .LBB0_166
	s_branch .Lkexit_0
	.p2align 3
	s_nop 0

; template <class Epi, class Sched, bool ALIGN_EPI = false, bool SP2 = false>
; __device__ __forceinline__ void gemm_phase(PG8_LAS unsigned char* lds, const Gemm g, const Sched& S, const Epi& E) {
;     ...
; #pragma unroll
;         for (int a = 0; a < 2; ++a)
; #pragma unroll
;             for (int b = 0; b < 2; ++b)
; #pragma unroll
;                 for (int m = 0; m < 4; ++m)
; #pragma unroll
;                     for (int n = 0; n < 2; ++n) acc[a][b][m][n] = (f32x4){0.f, 0.f, 0.f, 0.f};
.LBB0_193:
	s_add_u32 s59, s40, 0x100
	v_mov_b32_e32 v2, 0
	s_addc_u32 s69, s41, 0
	s_mov_b32 s70, -2
	s_waitcnt lgkmcnt(0)
	v_mov_b32_e32 v3, v2
	v_mov_b32_e32 v4, v2
	v_mov_b32_e32 v5, v2
	v_mov_b32_e32 v6, v2
	v_mov_b32_e32 v7, v2
	v_mov_b32_e32 v8, v2
	v_mov_b32_e32 v9, v2
	v_mov_b32_e32 v18, v2
	v_mov_b32_e32 v19, v2
	v_mov_b32_e32 v20, v2
	v_mov_b32_e32 v21, v2
	v_mov_b32_e32 v22, v2
	v_mov_b32_e32 v23, v2
	v_mov_b32_e32 v24, v2
	v_mov_b32_e32 v25, v2
	v_mov_b32_e32 v34, v2
	v_mov_b32_e32 v35, v2
	v_mov_b32_e32 v36, v2
	v_mov_b32_e32 v37, v2
	v_mov_b32_e32 v38, v2
	v_mov_b32_e32 v39, v2
	v_mov_b32_e32 v40, v2
	v_mov_b32_e32 v41, v2
	v_mov_b32_e32 v50, v2
	v_mov_b32_e32 v51, v2
	v_mov_b32_e32 v52, v2
	v_mov_b32_e32 v53, v2
	v_mov_b32_e32 v54, v2
	v_mov_b32_e32 v55, v2
	v_mov_b32_e32 v56, v2
	v_mov_b32_e32 v57, v2
	v_mov_b32_e32 v10, v2
	v_mov_b32_e32 v11, v2
	v_mov_b32_e32 v12, v2
	v_mov_b32_e32 v13, v2
	v_mov_b32_e32 v14, v2
	v_mov_b32_e32 v15, v2
	v_mov_b32_e32 v16, v2
	v_mov_b32_e32 v17, v2
	v_mov_b32_e32 v26, v2
	v_mov_b32_e32 v27, v2
	v_mov_b32_e32 v28, v2
	v_mov_b32_e32 v29, v2
	v_mov_b32_e32 v30, v2
	v_mov_b32_e32 v31, v2
	v_mov_b32_e32 v32, v2
	v_mov_b32_e32 v33, v2
	v_mov_b32_e32 v42, v2
	v_mov_b32_e32 v43, v2
	v_mov_b32_e32 v44, v2
	v_mov_b32_e32 v45, v2
	v_mov_b32_e32 v46, v2
	v_mov_b32_e32 v47, v2
	v_mov_b32_e32 v48, v2
	v_mov_b32_e32 v49, v2
	v_mov_b32_e32 v58, v2
	v_mov_b32_e32 v59, v2
	v_mov_b32_e32 v60, v2
	v_mov_b32_e32 v61, v2
	v_mov_b32_e32 v62, v2
	v_mov_b32_e32 v63, v2
	v_mov_b32_e32 v64, v2
	v_mov_b32_e32 v65, v2
	v_mov_b32_e32 v66, v2
	v_mov_b32_e32 v67, v2
	v_mov_b32_e32 v68, v2
	v_mov_b32_e32 v69, v2
	v_mov_b32_e32 v70, v2
	v_mov_b32_e32 v71, v2
	v_mov_b32_e32 v72, v2
	v_mov_b32_e32 v73, v2
	v_mov_b32_e32 v82, v2
	v_mov_b32_e32 v83, v2
	v_mov_b32_e32 v84, v2
	v_mov_b32_e32 v85, v2
	v_mov_b32_e32 v86, v2
	v_mov_b32_e32 v87, v2
	v_mov_b32_e32 v88, v2
	v_mov_b32_e32 v89, v2
	v_mov_b32_e32 v98, v2
	v_mov_b32_e32 v99, v2
	v_mov_b32_e32 v100, v2
	v_mov_b32_e32 v101, v2
	v_mov_b32_e32 v102, v2
	v_mov_b32_e32 v103, v2
	v_mov_b32_e32 v104, v2
	v_mov_b32_e32 v105, v2
	v_mov_b32_e32 v114, v2
	v_mov_b32_e32 v115, v2
	v_mov_b32_e32 v116, v2
	v_mov_b32_e32 v117, v2
	v_mov_b32_e32 v118, v2
	v_mov_b32_e32 v119, v2
	v_mov_b32_e32 v120, v2
	v_mov_b32_e32 v121, v2
	v_mov_b32_e32 v74, v2
	v_mov_b32_e32 v75, v2
	v_mov_b32_e32 v76, v2
	v_mov_b32_e32 v77, v2
	v_mov_b32_e32 v78, v2
	v_mov_b32_e32 v79, v2
	v_mov_b32_e32 v80, v2
	v_mov_b32_e32 v81, v2
	v_mov_b32_e32 v90, v2
	v_mov_b32_e32 v91, v2
	v_mov_b32_e32 v92, v2
	v_mov_b32_e32 v93, v2
	v_mov_b32_e32 v94, v2
	v_mov_b32_e32 v95, v2
	v_mov_b32_e32 v96, v2
	v_mov_b32_e32 v97, v2
	v_mov_b32_e32 v106, v2
	v_mov_b32_e32 v107, v2
	v_mov_b32_e32 v108, v2
	v_mov_b32_e32 v109, v2
	v_mov_b32_e32 v110, v2
	v_mov_b32_e32 v111, v2
	v_mov_b32_e32 v112, v2
	v_mov_b32_e32 v113, v2
	v_mov_b32_e32 v122, v2
	v_mov_b32_e32 v123, v2
	v_mov_b32_e32 v124, v2
	v_mov_b32_e32 v125, v2
	v_mov_b32_e32 v126, v2
	v_mov_b32_e32 v127, v2
	v_mov_b32_e32 v128, v2
	v_mov_b32_e32 v129, v2
	.p2align 3
	s_nop 0

; #define PG8_STAGE(bufoff, gbase, voff) do { _Pragma("unroll") for (int _i = 0; _i < 2; ++_i) \
;         __builtin_amdgcn_global_load_lds((const unsigned*)((const char*)(gbase) + (voff)[_i]), (PG8_LAS unsigned*)(lds + (bufoff) + ldsw + _i * 8192), 16, 0, 0); } while (0)
; #define PG8_LDA(dst, b, h) do { _Pragma("unroll") for (int m = 0; m < 4; ++m) _Pragma("unroll") for (int k = 0; k < 2; ++k) dst[m][k] = *(const PG8_LAS bf16x8*)(lds + PG8_SA(b, h) + aoff + m * 2048 + k * 1024); } while (0)
; #define PG8_LDB(dst, b, h) do { _Pragma("unroll") for (int n = 0; n < 2; ++n) _Pragma("unroll") for (int k = 0; k < 2; ++k) dst[n][k] = *(const PG8_LAS bf16x8*)(lds + PG8_SB(b, h) + boff + n * 2048 + k * 1024); } while (0)
; #define PG8_MMA_NP(ai, bj, At, Bt) do { _Pragma("unroll") for (int m = 0; m < 4; ++m) _Pragma("unroll") for (int n = 0; n < 2; ++n) _Pragma("unroll") for (int k = 0; k < 2; ++k) \
;         acc[ai][bj][m][n] = __builtin_amdgcn_mfma_f32_16x16x32_bf16(Bt[n][k], At[m][k], acc[ai][bj][m][n], 0, 0, 0); } while (0)
; template <class Epi, class Sched, bool ALIGN_EPI = false, bool SP2 = false>
; __device__ __forceinline__ void gemm_phase(PG8_LAS unsigned char* lds, const Gemm g, const Sched& S, const Epi& E) {
;     ...
;         const bool has_next = S.next(ui + 1, nxt);
;         const char* nA = has_next ? (const char*)g.A + (size_t)nxt.pm * tstep : cA; const char* nB = has_next ? (const char*)g.Bt + (size_t)nxt.pn * tstep : cB;
;         for (int t = 0; t < nt; t += 2) {
;             const bool last = (t == nt - 2);
;             const char* a1 = cA + (size_t)(t + 1) * kstep;
;             const char* a2 = last ? nA : cA + (size_t)(t + 2) * kstep; const char* b2 = last ? nB : cB + (size_t)(t + 2) * kstep;
;             const char* a3 = a2 + kstep; const char* b3 = b2 + kstep;
;             if (last && has_next) S.a_ready(nxt);
;             if constexpr (SP2) {
;             PG8_LDB(B0, 0, 0); PG8_LDB(B1, 0, 1); PG8_SCHED; PG8_LDA(At, 0, 0); PG8_STAGE(PG8_SA(1, 1), a1 + hstep, voffA);
;             PG8_WAIT_V(8); PG8_WAIT_L(0); PG8_BAR; __builtin_amdgcn_s_setprio(1); PG8_MMA_NP(0, 0, At, B0); PG8_MMA_NP(0, 1, At, B1); __builtin_amdgcn_s_setprio(0); PG8_BAR; PG8_SCHED;
;             PG8_LDA(At, 0, 1); PG8_STAGE(PG8_SB(0, 0), b2, voffB); PG8_STAGE(PG8_SB(0, 1), b2 + hstep, voffB); PG8_STAGE(PG8_SA(0, 0), a2, voffA);
.LBB0_369:
	s_ashr_i32 s55, s54, 31
	s_lshl_b64 s[40:41], s[54:55], 19
	s_add_u32 s56, s86, s40
	s_addc_u32 s57, s87, s41
	s_and_b64 s[40:41], s[42:43], exec
	s_cselect_b32 s46, s57, s13
	s_cselect_b32 s47, s56, s12
	s_ashr_i32 s53, s52, 31
	s_lshl_b64 s[40:41], s[52:53], 19
	s_add_u32 s58, s8, s40
	s_addc_u32 s59, s10, s41
	s_and_b64 s[40:41], s[42:43], exec
	s_cselect_b32 s48, s59, s15
	s_cselect_b32 s49, s58, s14
	s_add_u32 s12, s12, 0x40080
	s_addc_u32 s13, s13, 0
	s_add_u32 s53, s14, 0x100
	s_addc_u32 s55, s15, 0
	s_mov_b32 s65, -2
	s_add_u32 s14, s12, 0xfffc0080
	s_addc_u32 s15, s13, -1
	s_add_i32 s22, 0, 0x10000
	s_cmp_eq_u32 s65, 12
	s_cselect_b32 s41, s46, s15
	s_cselect_b32 s40, s47, s14
	s_cselect_b32 s15, s48, s55
	s_cselect_b32 s14, s49, s53
	s_add_i32 s23, 0, 0x14000
	v_add_u32_e32 v154, s22, v191
	v_add_u32_e32 v162, s23, v191
	ds_read_b128 v[130:133], v154
	ds_read_b128 v[146:149], v154 offset:1024
	ds_read_b128 v[150:153], v154 offset:2048
	ds_read_b128 v[154:157], v154 offset:3072
	ds_read_b128 v[158:161], v162
	ds_read_b128 v[178:181], v162 offset:1024
	ds_read_b128 v[182:185], v162 offset:2048
	ds_read_b128 v[186:189], v162 offset:3072
	v_lshl_add_u64 v[162:163], s[12:13], 0, v[142:143]
	s_add_i32 m0, s30, 0xc000
	ds_read_b128 v[204:207], v203
	ds_read_b128 v[208:211], v203 offset:1024
	ds_read_b128 v[212:215], v203 offset:2048
	ds_read_b128 v[216:219], v203 offset:3072
	ds_read_b128 v[220:223], v203 offset:4096
	ds_read_b128 v[224:227], v203 offset:5120
	ds_read_b128 v[228:231], v203 offset:6144
	ds_read_b128 v[232:235], v203 offset:7168
	global_load_lds_dwordx4 v[162:163], off
	v_lshl_add_u64 v[162:163], s[12:13], 0, v[144:145]
	s_add_i32 m0, s30, 0xe000
	s_nop 0
	global_load_lds_dwordx4 v[162:163], off
	s_waitcnt vmcnt(8)
	s_waitcnt lgkmcnt(0)
	s_barrier
	s_setprio 1
	s_waitcnt lgkmcnt(0)
	v_mfma_f32_16x16x32_bf16 v[126:129], v[130:133], v[204:207], 0
	v_mfma_f32_16x16x32_bf16 v[122:125], v[150:153], v[204:207], 0
	v_mfma_f32_16x16x32_bf16 v[110:113], v[130:133], v[212:215], 0
	v_mfma_f32_16x16x32_bf16 v[106:109], v[150:153], v[212:215], 0
	v_mfma_f32_16x16x32_bf16 v[94:97], v[130:133], v[220:223], 0
	v_mfma_f32_16x16x32_bf16 v[90:93], v[150:153], v[220:223], 0
	v_mfma_f32_16x16x32_bf16 v[78:81], v[130:133], v[228:231], 0
	v_mfma_f32_16x16x32_bf16 v[74:77], v[150:153], v[228:231], 0
	v_mfma_f32_16x16x32_bf16 v[118:121], v[158:161], v[204:207], 0
	v_mfma_f32_16x16x32_bf16 v[114:117], v[182:185], v[204:207], 0
	v_mfma_f32_16x16x32_bf16 v[102:105], v[158:161], v[212:215], 0
	v_mfma_f32_16x16x32_bf16 v[98:101], v[182:185], v[212:215], 0
	v_mfma_f32_16x16x32_bf16 v[86:89], v[158:161], v[220:223], 0
	v_mfma_f32_16x16x32_bf16 v[82:85], v[182:185], v[220:223], 0
	v_mfma_f32_16x16x32_bf16 v[70:73], v[158:161], v[228:231], 0
	v_mfma_f32_16x16x32_bf16 v[66:69], v[182:185], v[228:231], 0
	v_mfma_f32_16x16x32_bf16 v[126:129], v[146:149], v[208:211], v[126:129]
	v_mfma_f32_16x16x32_bf16 v[122:125], v[154:157], v[208:211], v[122:125]
	v_mfma_f32_16x16x32_bf16 v[110:113], v[146:149], v[216:219], v[110:113]
	v_mfma_f32_16x16x32_bf16 v[106:109], v[154:157], v[216:219], v[106:109]
	v_mfma_f32_16x16x32_bf16 v[94:97], v[146:149], v[224:227], v[94:97]
	v_mfma_f32_16x16x32_bf16 v[90:93], v[154:157], v[224:227], v[90:93]
	v_mfma_f32_16x16x32_bf16 v[78:81], v[146:149], v[232:235], v[78:81]
	v_mfma_f32_16x16x32_bf16 v[74:77], v[154:157], v[232:235], v[74:77]
	v_mfma_f32_16x16x32_bf16 v[118:121], v[178:181], v[208:211], v[118:121]
	v_mfma_f32_16x16x32_bf16 v[114:117], v[186:189], v[208:211], v[114:117]
	v_mfma_f32_16x16x32_bf16 v[102:105], v[178:181], v[216:219], v[102:105]
	v_mfma_f32_16x16x32_bf16 v[98:101], v[186:189], v[216:219], v[98:101]
	v_mfma_f32_16x16x32_bf16 v[86:89], v[178:181], v[224:227], v[86:89]
	v_mfma_f32_16x16x32_bf16 v[82:85], v[186:189], v[224:227], v[82:85]
	v_mfma_f32_16x16x32_bf16 v[70:73], v[178:181], v[232:235], v[70:73]
	v_mfma_f32_16x16x32_bf16 v[66:69], v[186:189], v[232:235], v[66:69]
	s_setprio 0
	s_barrier
	s_add_i32 s22, s22, s29
	v_lshl_add_u64 v[162:163], s[14:15], 0, v[0:1]
	s_mov_b32 m0, s22
	ds_read_b128 v[204:207], v203 offset:16384
	ds_read_b128 v[208:211], v203 offset:17408
	ds_read_b128 v[212:215], v203 offset:18432
	ds_read_b128 v[216:219], v203 offset:19456
	ds_read_b128 v[220:223], v203 offset:20480
	ds_read_b128 v[224:227], v203 offset:21504
	ds_read_b128 v[228:231], v203 offset:22528
	ds_read_b128 v[232:235], v203 offset:23552
	global_load_lds_dwordx4 v[162:163], off
	s_add_i32 m0, s22, 0x2000
	s_add_u32 s66, s14, 0x40000
	v_lshl_add_u64 v[236:237], s[14:15], 0, v[134:135]
	s_addc_u32 s67, s15, 0
	s_add_i32 s22, s23, s29
	global_load_lds_dwordx4 v[236:237], off
	v_lshl_add_u64 v[238:239], s[66:67], 0, v[0:1]
	s_mov_b32 m0, s22
	v_lshl_add_u64 v[240:241], s[40:41], 0, v[136:137]
	global_load_lds_dwordx4 v[238:239], off
	v_lshl_add_u64 v[238:239], s[66:67], 0, v[134:135]
	s_add_i32 m0, s22, 0x2000
	s_nop 0
	global_load_lds_dwordx4 v[238:239], off
	v_lshl_add_u64 v[238:239], s[40:41], 0, v[138:139]
	s_mov_b32 m0, s30
	s_nop 0
	global_load_lds_dwordx4 v[238:239], off
	s_mov_b32 m0, s31
	s_nop 0
	global_load_lds_dwordx4 v[240:241], off
	s_waitcnt vmcnt(8)
	s_waitcnt lgkmcnt(0)
	s_barrier
; #define PG8_STAGE(bufoff, gbase, voff) do { _Pragma("unroll") for (int _i = 0; _i < 2; ++_i) \
;         __builtin_amdgcn_global_load_lds((const unsigned*)((const char*)(gbase) + (voff)[_i]), (PG8_LAS unsigned*)(lds + (bufoff) + ldsw + _i * 8192), 16, 0, 0); } while (0)
; #define PG8_LDA(dst, b, h) do { _Pragma("unroll") for (int m = 0; m < 4; ++m) _Pragma("unroll") for (int k = 0; k < 2; ++k) dst[m][k] = *(const PG8_LAS bf16x8*)(lds + PG8_SA(b, h) + aoff + m * 2048 + k * 1024); } while (0)
; #define PG8_LDB(dst, b, h) do { _Pragma("unroll") for (int n = 0; n < 2; ++n) _Pragma("unroll") for (int k = 0; k < 2; ++k) dst[n][k] = *(const PG8_LAS bf16x8*)(lds + PG8_SB(b, h) + boff + n * 2048 + k * 1024); } while (0)
; #define PG8_MMA_NP(ai, bj, At, Bt) do { _Pragma("unroll") for (int m = 0; m < 4; ++m) _Pragma("unroll") for (int n = 0; n < 2; ++n) _Pragma("unroll") for (int k = 0; k < 2; ++k) \
;         acc[ai][bj][m][n] = __builtin_amdgcn_mfma_f32_16x16x32_bf16(Bt[n][k], At[m][k], acc[ai][bj][m][n], 0, 0, 0); } while (0)
; #define PG8_WAIT_V(n) asm volatile("s_waitcnt vmcnt(" #n ")" ::: "memory")
; #define PG8_WAIT_L(n) asm volatile("s_waitcnt lgkmcnt(" #n ")" ::: "memory")
; #define PG8_BAR __builtin_amdgcn_s_barrier()
; #define PG8_SCHED __builtin_amdgcn_sched_barrier(0)
; template <class Epi, class Sched, bool ALIGN_EPI = false, bool SP2 = false>
; __device__ __forceinline__ void gemm_phase(PG8_LAS unsigned char* lds, const Gemm g, const Sched& S, const Epi& E) {
;     ...
;             PG8_WAIT_V(8); PG8_WAIT_L(0); PG8_BAR; __builtin_amdgcn_s_setprio(1); PG8_MMA_NP(1, 0, At, B0); PG8_MMA_NP(1, 1, At, B1); __builtin_amdgcn_s_setprio(0); PG8_BAR; PG8_SCHED;
;             PG8_LDB(B0, 1, 0); PG8_LDB(B1, 1, 1); PG8_SCHED; PG8_LDA(At, 1, 0); PG8_STAGE(PG8_SA(0, 1), a2 + hstep, voffA);
;             PG8_WAIT_V(8); PG8_WAIT_L(0); PG8_BAR; __builtin_amdgcn_s_setprio(1); PG8_MMA_NP(0, 0, At, B0); PG8_MMA_NP(0, 1, At, B1); __builtin_amdgcn_s_setprio(0); PG8_BAR; PG8_SCHED;
	s_setprio 1
	s_waitcnt lgkmcnt(0)
	v_mfma_f32_16x16x32_bf16 v[62:65], v[130:133], v[204:207], 0
	v_mfma_f32_16x16x32_bf16 v[58:61], v[150:153], v[204:207], 0
	v_mfma_f32_16x16x32_bf16 v[46:49], v[130:133], v[212:215], 0
	v_mfma_f32_16x16x32_bf16 v[42:45], v[150:153], v[212:215], 0
	v_mfma_f32_16x16x32_bf16 v[30:33], v[130:133], v[220:223], 0
	v_mfma_f32_16x16x32_bf16 v[26:29], v[150:153], v[220:223], 0
	v_mfma_f32_16x16x32_bf16 v[14:17], v[130:133], v[228:231], 0
	v_mfma_f32_16x16x32_bf16 v[10:13], v[150:153], v[228:231], 0
	v_mfma_f32_16x16x32_bf16 v[54:57], v[158:161], v[204:207], 0
	v_mfma_f32_16x16x32_bf16 v[50:53], v[182:185], v[204:207], 0
	v_mfma_f32_16x16x32_bf16 v[38:41], v[158:161], v[212:215], 0
	v_mfma_f32_16x16x32_bf16 v[34:37], v[182:185], v[212:215], 0
	v_mfma_f32_16x16x32_bf16 v[22:25], v[158:161], v[220:223], 0
	v_mfma_f32_16x16x32_bf16 v[18:21], v[182:185], v[220:223], 0
	v_mfma_f32_16x16x32_bf16 v[6:9], v[158:161], v[228:231], 0
	v_mfma_f32_16x16x32_bf16 v[2:5], v[182:185], v[228:231], 0
	v_mfma_f32_16x16x32_bf16 v[62:65], v[146:149], v[208:211], v[62:65]
	v_mfma_f32_16x16x32_bf16 v[58:61], v[154:157], v[208:211], v[58:61]
	v_mfma_f32_16x16x32_bf16 v[46:49], v[146:149], v[216:219], v[46:49]
	v_mfma_f32_16x16x32_bf16 v[42:45], v[154:157], v[216:219], v[42:45]
	v_mfma_f32_16x16x32_bf16 v[30:33], v[146:149], v[224:227], v[30:33]
	v_mfma_f32_16x16x32_bf16 v[26:29], v[154:157], v[224:227], v[26:29]
	v_mfma_f32_16x16x32_bf16 v[14:17], v[146:149], v[232:235], v[14:17]
	v_mfma_f32_16x16x32_bf16 v[10:13], v[154:157], v[232:235], v[10:13]
	v_mfma_f32_16x16x32_bf16 v[54:57], v[178:181], v[208:211], v[54:57]
	v_mfma_f32_16x16x32_bf16 v[50:53], v[186:189], v[208:211], v[50:53]
	v_mfma_f32_16x16x32_bf16 v[38:41], v[178:181], v[216:219], v[38:41]
	v_mfma_f32_16x16x32_bf16 v[34:37], v[186:189], v[216:219], v[34:37]
	v_mfma_f32_16x16x32_bf16 v[22:25], v[178:181], v[224:227], v[22:25]
	v_mfma_f32_16x16x32_bf16 v[18:21], v[186:189], v[224:227], v[18:21]
	v_mfma_f32_16x16x32_bf16 v[6:9], v[178:181], v[232:235], v[6:9]
	v_mfma_f32_16x16x32_bf16 v[2:5], v[186:189], v[232:235], v[2:5]
	s_setprio 0
	s_barrier
	s_add_i32 s22, 0, 0x18000
	s_add_i32 s23, 0, 0x1c000
	v_add_u32_e32 v154, s22, v191
	v_add_u32_e32 v186, s23, v191
	ds_read_b128 v[130:133], v154
	ds_read_b128 v[146:149], v154 offset:1024
	ds_read_b128 v[150:153], v154 offset:2048
	ds_read_b128 v[154:157], v154 offset:3072
	ds_read_b128 v[158:161], v186
	ds_read_b128 v[178:181], v186 offset:1024
	ds_read_b128 v[182:185], v186 offset:2048
	ds_read_b128 v[186:189], v186 offset:3072
	s_add_u32 s40, s40, 0x40000
	s_addc_u32 s41, s41, 0
	s_mov_b32 m0, s60
	v_lshl_add_u64 v[242:243], s[40:41], 0, v[138:139]
	ds_read_b128 v[204:207], v203 offset:32768
	ds_read_b128 v[208:211], v203 offset:33792
	ds_read_b128 v[212:215], v203 offset:34816
	ds_read_b128 v[216:219], v203 offset:35840
	ds_read_b128 v[220:223], v203 offset:36864
	ds_read_b128 v[224:227], v203 offset:37888
	ds_read_b128 v[228:231], v203 offset:38912
	ds_read_b128 v[232:235], v203 offset:39936
	global_load_lds_dwordx4 v[242:243], off
	v_lshl_add_u64 v[242:243], s[40:41], 0, v[136:137]
	s_mov_b32 m0, s61
	s_nop 0
	global_load_lds_dwordx4 v[242:243], off
	s_waitcnt vmcnt(8)
	s_waitcnt lgkmcnt(0)
	s_barrier
	s_setprio 1
	s_waitcnt lgkmcnt(0)
	v_mfma_f32_16x16x32_bf16 v[126:129], v[130:133], v[204:207], v[126:129]
	v_mfma_f32_16x16x32_bf16 v[122:125], v[150:153], v[204:207], v[122:125]
	v_mfma_f32_16x16x32_bf16 v[110:113], v[130:133], v[212:215], v[110:113]
	v_mfma_f32_16x16x32_bf16 v[106:109], v[150:153], v[212:215], v[106:109]
	v_mfma_f32_16x16x32_bf16 v[94:97], v[130:133], v[220:223], v[94:97]
	v_mfma_f32_16x16x32_bf16 v[90:93], v[150:153], v[220:223], v[90:93]
	v_mfma_f32_16x16x32_bf16 v[78:81], v[130:133], v[228:231], v[78:81]
	v_mfma_f32_16x16x32_bf16 v[74:77], v[150:153], v[228:231], v[74:77]
	v_mfma_f32_16x16x32_bf16 v[118:121], v[158:161], v[204:207], v[118:121]
	v_mfma_f32_16x16x32_bf16 v[114:117], v[182:185], v[204:207], v[114:117]
	v_mfma_f32_16x16x32_bf16 v[102:105], v[158:161], v[212:215], v[102:105]
	v_mfma_f32_16x16x32_bf16 v[98:101], v[182:185], v[212:215], v[98:101]
	v_mfma_f32_16x16x32_bf16 v[86:89], v[158:161], v[220:223], v[86:89]
	v_mfma_f32_16x16x32_bf16 v[82:85], v[182:185], v[220:223], v[82:85]
	v_mfma_f32_16x16x32_bf16 v[70:73], v[158:161], v[228:231], v[70:73]
	v_mfma_f32_16x16x32_bf16 v[66:69], v[182:185], v[228:231], v[66:69]
	v_mfma_f32_16x16x32_bf16 v[126:129], v[146:149], v[208:211], v[126:129]
	v_mfma_f32_16x16x32_bf16 v[122:125], v[154:157], v[208:211], v[122:125]
	v_mfma_f32_16x16x32_bf16 v[110:113], v[146:149], v[216:219], v[110:113]
	v_mfma_f32_16x16x32_bf16 v[106:109], v[154:157], v[216:219], v[106:109]
	v_mfma_f32_16x16x32_bf16 v[94:97], v[146:149], v[224:227], v[94:97]
	v_mfma_f32_16x16x32_bf16 v[90:93], v[154:157], v[224:227], v[90:93]
	v_mfma_f32_16x16x32_bf16 v[78:81], v[146:149], v[232:235], v[78:81]
	v_mfma_f32_16x16x32_bf16 v[74:77], v[154:157], v[232:235], v[74:77]
	v_mfma_f32_16x16x32_bf16 v[118:121], v[178:181], v[208:211], v[118:121]
	v_mfma_f32_16x16x32_bf16 v[114:117], v[186:189], v[208:211], v[114:117]
	v_mfma_f32_16x16x32_bf16 v[102:105], v[178:181], v[216:219], v[102:105]
	v_mfma_f32_16x16x32_bf16 v[98:101], v[186:189], v[216:219], v[98:101]
	v_mfma_f32_16x16x32_bf16 v[86:89], v[178:181], v[224:227], v[86:89]
	v_mfma_f32_16x16x32_bf16 v[82:85], v[186:189], v[224:227], v[82:85]
	v_mfma_f32_16x16x32_bf16 v[70:73], v[178:181], v[232:235], v[70:73]
	v_mfma_f32_16x16x32_bf16 v[66:69], v[186:189], v[232:235], v[66:69]
	s_setprio 0
	s_barrier
; #define PG8_STAGE(bufoff, gbase, voff) do { _Pragma("unroll") for (int _i = 0; _i < 2; ++_i) \
;         __builtin_amdgcn_global_load_lds((const unsigned*)((const char*)(gbase) + (voff)[_i]), (PG8_LAS unsigned*)(lds + (bufoff) + ldsw + _i * 8192), 16, 0, 0); } while (0)
; #define PG8_LDA(dst, b, h) do { _Pragma("unroll") for (int m = 0; m < 4; ++m) _Pragma("unroll") for (int k = 0; k < 2; ++k) dst[m][k] = *(const PG8_LAS bf16x8*)(lds + PG8_SA(b, h) + aoff + m * 2048 + k * 1024); } while (0)
; #define PG8_MMA_NP(ai, bj, At, Bt) do { _Pragma("unroll") for (int m = 0; m < 4; ++m) _Pragma("unroll") for (int n = 0; n < 2; ++n) _Pragma("unroll") for (int k = 0; k < 2; ++k) \
;         acc[ai][bj][m][n] = __builtin_amdgcn_mfma_f32_16x16x32_bf16(Bt[n][k], At[m][k], acc[ai][bj][m][n], 0, 0, 0); } while (0)
; #define PG8_WAIT_V(n) asm volatile("s_waitcnt vmcnt(" #n ")" ::: "memory")
; #define PG8_WAIT_L(n) asm volatile("s_waitcnt lgkmcnt(" #n ")" ::: "memory")
; #define PG8_BAR __builtin_amdgcn_s_barrier()
; #define PG8_SCHED __builtin_amdgcn_sched_barrier(0)
; template <class Epi, class Sched, bool ALIGN_EPI = false, bool SP2 = false>
; __device__ __forceinline__ void gemm_phase(PG8_LAS unsigned char* lds, const Gemm g, const Sched& S, const Epi& E) {
;     ...
;         for (int t = 0; t < nt; t += 2) {
;     ...
;             PG8_LDA(At, 1, 1); PG8_STAGE(PG8_SB(1, 0), b3, voffB); PG8_STAGE(PG8_SB(1, 1), b3 + hstep, voffB); PG8_STAGE(PG8_SA(1, 0), a3, voffA);
;             PG8_WAIT_V(8); PG8_WAIT_L(0); PG8_BAR; __builtin_amdgcn_s_setprio(1); PG8_MMA_NP(1, 0, At, B0); PG8_MMA_NP(1, 1, At, B1); __builtin_amdgcn_s_setprio(0); PG8_BAR; PG8_SCHED;
	s_add_i32 s22, s22, s29
	v_lshl_add_u64 v[162:163], v[162:163], 0, s[20:21]
	s_mov_b32 m0, s22
	ds_read_b128 v[204:207], v203 offset:49152
	ds_read_b128 v[208:211], v203 offset:50176
	ds_read_b128 v[212:215], v203 offset:51200
	ds_read_b128 v[216:219], v203 offset:52224
	ds_read_b128 v[220:223], v203 offset:53248
	ds_read_b128 v[224:227], v203 offset:54272
	ds_read_b128 v[228:231], v203 offset:55296
	ds_read_b128 v[232:235], v203 offset:56320
	global_load_lds_dwordx4 v[162:163], off
	s_add_i32 m0, s22, 0x2000
	s_add_u32 s14, s14, 0x40080
	v_lshl_add_u64 v[162:163], v[236:237], 0, s[20:21]
	s_addc_u32 s15, s15, 0
	s_add_i32 s22, s23, s29
	global_load_lds_dwordx4 v[162:163], off
	v_lshl_add_u64 v[162:163], s[14:15], 0, v[0:1]
	s_mov_b32 m0, s22
	s_nop 0
	global_load_lds_dwordx4 v[162:163], off
	v_lshl_add_u64 v[162:163], s[14:15], 0, v[134:135]
	s_add_i32 m0, s22, 0x2000
	s_nop 0
	global_load_lds_dwordx4 v[162:163], off
	v_lshl_add_u64 v[162:163], v[238:239], 0, s[20:21]
	s_mov_b32 m0, s62
	s_nop 0
	global_load_lds_dwordx4 v[162:163], off
	v_lshl_add_u64 v[162:163], v[240:241], 0, s[20:21]
	s_mov_b32 m0, s63
	s_nop 0
	global_load_lds_dwordx4 v[162:163], off
	s_waitcnt vmcnt(8)
	s_waitcnt lgkmcnt(0)
	s_barrier
	s_setprio 1
	s_waitcnt lgkmcnt(0)
	v_mfma_f32_16x16x32_bf16 v[62:65], v[130:133], v[204:207], v[62:65]
	v_mfma_f32_16x16x32_bf16 v[58:61], v[150:153], v[204:207], v[58:61]
	v_mfma_f32_16x16x32_bf16 v[46:49], v[130:133], v[212:215], v[46:49]
	v_mfma_f32_16x16x32_bf16 v[42:45], v[150:153], v[212:215], v[42:45]
	v_mfma_f32_16x16x32_bf16 v[30:33], v[130:133], v[220:223], v[30:33]
	v_mfma_f32_16x16x32_bf16 v[26:29], v[150:153], v[220:223], v[26:29]
	v_mfma_f32_16x16x32_bf16 v[14:17], v[130:133], v[228:231], v[14:17]
	v_mfma_f32_16x16x32_bf16 v[10:13], v[150:153], v[228:231], v[10:13]
	v_mfma_f32_16x16x32_bf16 v[54:57], v[158:161], v[204:207], v[54:57]
	v_mfma_f32_16x16x32_bf16 v[50:53], v[182:185], v[204:207], v[50:53]
	v_mfma_f32_16x16x32_bf16 v[38:41], v[158:161], v[212:215], v[38:41]
	v_mfma_f32_16x16x32_bf16 v[34:37], v[182:185], v[212:215], v[34:37]
	v_mfma_f32_16x16x32_bf16 v[22:25], v[158:161], v[220:223], v[22:25]
	v_mfma_f32_16x16x32_bf16 v[18:21], v[182:185], v[220:223], v[18:21]
	v_mfma_f32_16x16x32_bf16 v[6:9], v[158:161], v[228:231], v[6:9]
	v_mfma_f32_16x16x32_bf16 v[2:5], v[182:185], v[228:231], v[2:5]
	v_mfma_f32_16x16x32_bf16 v[62:65], v[146:149], v[208:211], v[62:65]
	v_mfma_f32_16x16x32_bf16 v[58:61], v[154:157], v[208:211], v[58:61]
	v_mfma_f32_16x16x32_bf16 v[46:49], v[146:149], v[216:219], v[46:49]
	v_mfma_f32_16x16x32_bf16 v[42:45], v[154:157], v[216:219], v[42:45]
	v_mfma_f32_16x16x32_bf16 v[30:33], v[146:149], v[224:227], v[30:33]
	v_mfma_f32_16x16x32_bf16 v[26:29], v[154:157], v[224:227], v[26:29]
	v_mfma_f32_16x16x32_bf16 v[14:17], v[146:149], v[232:235], v[14:17]
	v_mfma_f32_16x16x32_bf16 v[10:13], v[154:157], v[232:235], v[10:13]
	v_mfma_f32_16x16x32_bf16 v[54:57], v[178:181], v[208:211], v[54:57]
	v_mfma_f32_16x16x32_bf16 v[50:53], v[186:189], v[208:211], v[50:53]
	v_mfma_f32_16x16x32_bf16 v[38:41], v[178:181], v[216:219], v[38:41]
	v_mfma_f32_16x16x32_bf16 v[34:37], v[186:189], v[216:219], v[34:37]
	v_mfma_f32_16x16x32_bf16 v[22:25], v[178:181], v[224:227], v[22:25]
	v_mfma_f32_16x16x32_bf16 v[18:21], v[186:189], v[224:227], v[18:21]
	v_mfma_f32_16x16x32_bf16 v[6:9], v[178:181], v[232:235], v[6:9]
	v_mfma_f32_16x16x32_bf16 v[2:5], v[186:189], v[232:235], v[2:5]
	s_setprio 0
	s_barrier
	s_add_i32 s65, s65, 2
	s_add_u32 s12, s12, 0x100
	s_addc_u32 s13, s13, 0
	s_add_u32 s53, s53, 0x100
	s_addc_u32 s55, s55, 0
	s_cmp_gt_u32 s65, 13
	s_cbranch_scc0 .LBB0_370
	s_branch .Lkexit_2
	.p2align 3
	s_nop 0

; #define PG8_STAGE(bufoff, gbase, voff) do { _Pragma("unroll") for (int _i = 0; _i < 2; ++_i) \
;         __builtin_amdgcn_global_load_lds((const unsigned*)((const char*)(gbase) + (voff)[_i]), (PG8_LAS unsigned*)(lds + (bufoff) + ldsw + _i * 8192), 16, 0, 0); } while (0)
; #define PG8_LDA(dst, b, h) do { _Pragma("unroll") for (int m = 0; m < 4; ++m) _Pragma("unroll") for (int k = 0; k < 2; ++k) dst[m][k] = *(const PG8_LAS bf16x8*)(lds + PG8_SA(b, h) + aoff + m * 2048 + k * 1024); } while (0)
; #define PG8_LDB(dst, b, h) do { _Pragma("unroll") for (int n = 0; n < 2; ++n) _Pragma("unroll") for (int k = 0; k < 2; ++k) dst[n][k] = *(const PG8_LAS bf16x8*)(lds + PG8_SB(b, h) + boff + n * 2048 + k * 1024); } while (0)
; #define PG8_MMA_NP(ai, bj, At, Bt) do { _Pragma("unroll") for (int m = 0; m < 4; ++m) _Pragma("unroll") for (int n = 0; n < 2; ++n) _Pragma("unroll") for (int k = 0; k < 2; ++k) \
;         acc[ai][bj][m][n] = __builtin_amdgcn_mfma_f32_16x16x32_bf16(Bt[n][k], At[m][k], acc[ai][bj][m][n], 0, 0, 0); } while (0)
; template <class Epi, class Sched, bool ALIGN_EPI = false, bool SP2 = false>
; __device__ __forceinline__ void gemm_phase(PG8_LAS unsigned char* lds, const Gemm g, const Sched& S, const Epi& E) {
;     ...
;         const bool has_next = S.next(ui + 1, nxt);
;         const char* nA = has_next ? (const char*)g.A + (size_t)nxt.pm * tstep : cA; const char* nB = has_next ? (const char*)g.Bt + (size_t)nxt.pn * tstep : cB;
;         for (int t = 0; t < nt; t += 2) {
;             const bool last = (t == nt - 2);
;             const char* a1 = cA + (size_t)(t + 1) * kstep;
;             const char* a2 = last ? nA : cA + (size_t)(t + 2) * kstep; const char* b2 = last ? nB : cB + (size_t)(t + 2) * kstep;
;             const char* a3 = a2 + kstep; const char* b3 = b2 + kstep;
;             if (last && has_next) S.a_ready(nxt);
;             if constexpr (SP2) {
;             PG8_LDB(B0, 0, 0); PG8_LDB(B1, 0, 1); PG8_SCHED; PG8_LDA(At, 0, 0); PG8_STAGE(PG8_SA(1, 1), a1 + hstep, voffA);
;             PG8_WAIT_V(8); PG8_WAIT_L(0); PG8_BAR; __builtin_amdgcn_s_setprio(1); PG8_MMA_NP(0, 0, At, B0); PG8_MMA_NP(0, 1, At, B1); __builtin_amdgcn_s_setprio(0); PG8_BAR; PG8_SCHED;
;             PG8_LDA(At, 0, 1); PG8_STAGE(PG8_SB(0, 0), b2, voffB); PG8_STAGE(PG8_SB(0, 1), b2 + hstep, voffB); PG8_STAGE(PG8_SA(0, 0), a2, voffA);
.LBB0_431:
	s_ashr_i32 s49, s48, 31
	s_lshl_b64 s[14:15], s[48:49], 19
	s_add_u32 s50, s10, s14
	s_addc_u32 s51, s29, s15
	s_and_b64 s[14:15], s[42:43], exec
	s_cselect_b32 s49, s51, s3
	s_cselect_b32 s59, s50, s2
	s_ashr_i32 s47, s46, 31
	s_lshl_b64 s[14:15], s[46:47], 19
	s_add_u32 s52, s86, s14
	s_addc_u32 s53, s87, s15
	s_and_b64 s[14:15], s[42:43], exec
	s_cselect_b32 s47, s53, s13
	s_cselect_b32 s60, s52, s12
	s_add_u32 s2, s2, 0x40080
	s_addc_u32 s3, s3, 0
	s_add_u32 s61, s12, 0x100
	s_addc_u32 s62, s13, 0
	s_mov_b32 s63, -2
	s_add_u32 s12, s2, 0xfffc0080
	s_addc_u32 s13, s3, -1
	s_add_i32 s22, 0, 0x10000
	s_cmp_eq_u32 s63, 12
	s_cselect_b32 s15, s49, s13
	s_cselect_b32 s14, s59, s12
	s_cselect_b32 s13, s47, s62
	s_cselect_b32 s12, s60, s61
	s_add_i32 s23, 0, 0x14000
	v_add_u32_e32 v154, s22, v159
	v_add_u32_e32 v162, s23, v159
	ds_read_b128 v[142:145], v154
	ds_read_b128 v[146:149], v154 offset:1024
	ds_read_b128 v[150:153], v154 offset:2048
	ds_read_b128 v[154:157], v154 offset:3072
	ds_read_b128 v[178:181], v162
	ds_read_b128 v[182:185], v162 offset:1024
	ds_read_b128 v[186:189], v162 offset:2048
	ds_read_b128 v[202:205], v162 offset:3072
	v_lshl_add_u64 v[162:163], s[2:3], 0, v[138:139]
	s_add_i32 m0, s30, 0xc000
	ds_read_b128 v[206:209], v161
	ds_read_b128 v[210:213], v161 offset:1024
	ds_read_b128 v[214:217], v161 offset:2048
	ds_read_b128 v[218:221], v161 offset:3072
	ds_read_b128 v[222:225], v161 offset:4096
	ds_read_b128 v[226:229], v161 offset:5120
	ds_read_b128 v[230:233], v161 offset:6144
	ds_read_b128 v[234:237], v161 offset:7168
	global_load_lds_dwordx4 v[162:163], off
	v_lshl_add_u64 v[162:163], s[2:3], 0, v[140:141]
	s_add_i32 m0, s30, 0xe000
	s_nop 0
	global_load_lds_dwordx4 v[162:163], off
	s_waitcnt vmcnt(8)
	s_waitcnt lgkmcnt(0)
	s_barrier
	s_setprio 1
	s_waitcnt lgkmcnt(0)
	v_mfma_f32_16x16x32_bf16 v[126:129], v[142:145], v[206:209], 0
	v_mfma_f32_16x16x32_bf16 v[122:125], v[150:153], v[206:209], 0
	v_mfma_f32_16x16x32_bf16 v[118:121], v[142:145], v[214:217], 0
	v_mfma_f32_16x16x32_bf16 v[114:117], v[150:153], v[214:217], 0
	v_mfma_f32_16x16x32_bf16 v[110:113], v[142:145], v[222:225], 0
	v_mfma_f32_16x16x32_bf16 v[106:109], v[150:153], v[222:225], 0
	v_mfma_f32_16x16x32_bf16 v[102:105], v[142:145], v[230:233], 0
	v_mfma_f32_16x16x32_bf16 v[98:101], v[150:153], v[230:233], 0
	v_mfma_f32_16x16x32_bf16 v[62:65], v[178:181], v[206:209], 0
	v_mfma_f32_16x16x32_bf16 v[58:61], v[186:189], v[206:209], 0
	v_mfma_f32_16x16x32_bf16 v[54:57], v[178:181], v[214:217], 0
	v_mfma_f32_16x16x32_bf16 v[50:53], v[186:189], v[214:217], 0
	v_mfma_f32_16x16x32_bf16 v[46:49], v[178:181], v[222:225], 0
	v_mfma_f32_16x16x32_bf16 v[42:45], v[186:189], v[222:225], 0
	v_mfma_f32_16x16x32_bf16 v[38:41], v[178:181], v[230:233], 0
	v_mfma_f32_16x16x32_bf16 v[34:37], v[186:189], v[230:233], 0
	v_mfma_f32_16x16x32_bf16 v[126:129], v[146:149], v[210:213], v[126:129]
	v_mfma_f32_16x16x32_bf16 v[122:125], v[154:157], v[210:213], v[122:125]
	v_mfma_f32_16x16x32_bf16 v[118:121], v[146:149], v[218:221], v[118:121]
	v_mfma_f32_16x16x32_bf16 v[114:117], v[154:157], v[218:221], v[114:117]
	v_mfma_f32_16x16x32_bf16 v[110:113], v[146:149], v[226:229], v[110:113]
	v_mfma_f32_16x16x32_bf16 v[106:109], v[154:157], v[226:229], v[106:109]
	v_mfma_f32_16x16x32_bf16 v[102:105], v[146:149], v[234:237], v[102:105]
	v_mfma_f32_16x16x32_bf16 v[98:101], v[154:157], v[234:237], v[98:101]
	v_mfma_f32_16x16x32_bf16 v[62:65], v[182:185], v[210:213], v[62:65]
	v_mfma_f32_16x16x32_bf16 v[58:61], v[202:205], v[210:213], v[58:61]
	v_mfma_f32_16x16x32_bf16 v[54:57], v[182:185], v[218:221], v[54:57]
	v_mfma_f32_16x16x32_bf16 v[50:53], v[202:205], v[218:221], v[50:53]
	v_mfma_f32_16x16x32_bf16 v[46:49], v[182:185], v[226:229], v[46:49]
	v_mfma_f32_16x16x32_bf16 v[42:45], v[202:205], v[226:229], v[42:45]
	v_mfma_f32_16x16x32_bf16 v[38:41], v[182:185], v[234:237], v[38:41]
	v_mfma_f32_16x16x32_bf16 v[34:37], v[202:205], v[234:237], v[34:37]
	s_setprio 0
	s_barrier
	s_add_i32 s22, s22, s8
	v_lshl_add_u64 v[162:163], s[12:13], 0, v[0:1]
	s_mov_b32 m0, s22
	ds_read_b128 v[206:209], v161 offset:16384
	ds_read_b128 v[210:213], v161 offset:17408
	ds_read_b128 v[214:217], v161 offset:18432
	ds_read_b128 v[218:221], v161 offset:19456
	ds_read_b128 v[222:225], v161 offset:20480
	ds_read_b128 v[226:229], v161 offset:21504
	ds_read_b128 v[230:233], v161 offset:22528
	ds_read_b128 v[234:237], v161 offset:23552
	global_load_lds_dwordx4 v[162:163], off
	s_add_i32 m0, s22, 0x2000
	s_add_u32 s64, s12, 0x40000
	v_lshl_add_u64 v[190:191], s[12:13], 0, v[130:131]
	s_addc_u32 s65, s13, 0
	s_add_i32 s22, s23, s8
	global_load_lds_dwordx4 v[190:191], off
	v_lshl_add_u64 v[238:239], s[64:65], 0, v[0:1]
	s_mov_b32 m0, s22
	v_lshl_add_u64 v[240:241], s[14:15], 0, v[132:133]
	global_load_lds_dwordx4 v[238:239], off
	v_lshl_add_u64 v[238:239], s[64:65], 0, v[130:131]
	s_add_i32 m0, s22, 0x2000
	s_nop 0
	global_load_lds_dwordx4 v[238:239], off
	v_lshl_add_u64 v[238:239], s[14:15], 0, v[134:135]
	s_mov_b32 m0, s30
	s_nop 0
	global_load_lds_dwordx4 v[238:239], off
	s_mov_b32 m0, s31
	s_nop 0
	global_load_lds_dwordx4 v[240:241], off
	s_waitcnt vmcnt(8)
	s_waitcnt lgkmcnt(0)
	s_barrier
; #define PG8_STAGE(bufoff, gbase, voff) do { _Pragma("unroll") for (int _i = 0; _i < 2; ++_i) \
;         __builtin_amdgcn_global_load_lds((const unsigned*)((const char*)(gbase) + (voff)[_i]), (PG8_LAS unsigned*)(lds + (bufoff) + ldsw + _i * 8192), 16, 0, 0); } while (0)
; #define PG8_LDA(dst, b, h) do { _Pragma("unroll") for (int m = 0; m < 4; ++m) _Pragma("unroll") for (int k = 0; k < 2; ++k) dst[m][k] = *(const PG8_LAS bf16x8*)(lds + PG8_SA(b, h) + aoff + m * 2048 + k * 1024); } while (0)
; #define PG8_LDB(dst, b, h) do { _Pragma("unroll") for (int n = 0; n < 2; ++n) _Pragma("unroll") for (int k = 0; k < 2; ++k) dst[n][k] = *(const PG8_LAS bf16x8*)(lds + PG8_SB(b, h) + boff + n * 2048 + k * 1024); } while (0)
; #define PG8_MMA_NP(ai, bj, At, Bt) do { _Pragma("unroll") for (int m = 0; m < 4; ++m) _Pragma("unroll") for (int n = 0; n < 2; ++n) _Pragma("unroll") for (int k = 0; k < 2; ++k) \
;         acc[ai][bj][m][n] = __builtin_amdgcn_mfma_f32_16x16x32_bf16(Bt[n][k], At[m][k], acc[ai][bj][m][n], 0, 0, 0); } while (0)
; #define PG8_WAIT_V(n) asm volatile("s_waitcnt vmcnt(" #n ")" ::: "memory")
; #define PG8_WAIT_L(n) asm volatile("s_waitcnt lgkmcnt(" #n ")" ::: "memory")
; #define PG8_BAR __builtin_amdgcn_s_barrier()
; #define PG8_SCHED __builtin_amdgcn_sched_barrier(0)
; template <class Epi, class Sched, bool ALIGN_EPI = false, bool SP2 = false>
; __device__ __forceinline__ void gemm_phase(PG8_LAS unsigned char* lds, const Gemm g, const Sched& S, const Epi& E) {
;     ...
;             PG8_WAIT_V(8); PG8_WAIT_L(0); PG8_BAR; __builtin_amdgcn_s_setprio(1); PG8_MMA_NP(1, 0, At, B0); PG8_MMA_NP(1, 1, At, B1); __builtin_amdgcn_s_setprio(0); PG8_BAR; PG8_SCHED;
;             PG8_LDB(B0, 1, 0); PG8_LDB(B1, 1, 1); PG8_SCHED; PG8_LDA(At, 1, 0); PG8_STAGE(PG8_SA(0, 1), a2 + hstep, voffA);
;             PG8_WAIT_V(8); PG8_WAIT_L(0); PG8_BAR; __builtin_amdgcn_s_setprio(1); PG8_MMA_NP(0, 0, At, B0); PG8_MMA_NP(0, 1, At, B1); __builtin_amdgcn_s_setprio(0); PG8_BAR; PG8_SCHED;
	s_setprio 1
	s_waitcnt lgkmcnt(0)
	v_mfma_f32_16x16x32_bf16 v[94:97], v[142:145], v[206:209], 0
	v_mfma_f32_16x16x32_bf16 v[90:93], v[150:153], v[206:209], 0
	v_mfma_f32_16x16x32_bf16 v[86:89], v[142:145], v[214:217], 0
	v_mfma_f32_16x16x32_bf16 v[82:85], v[150:153], v[214:217], 0
	v_mfma_f32_16x16x32_bf16 v[78:81], v[142:145], v[222:225], 0
	v_mfma_f32_16x16x32_bf16 v[74:77], v[150:153], v[222:225], 0
	v_mfma_f32_16x16x32_bf16 v[70:73], v[142:145], v[230:233], 0
	v_mfma_f32_16x16x32_bf16 v[66:69], v[150:153], v[230:233], 0
	v_mfma_f32_16x16x32_bf16 v[30:33], v[178:181], v[206:209], 0
	v_mfma_f32_16x16x32_bf16 v[26:29], v[186:189], v[206:209], 0
	v_mfma_f32_16x16x32_bf16 v[22:25], v[178:181], v[214:217], 0
	v_mfma_f32_16x16x32_bf16 v[18:21], v[186:189], v[214:217], 0
	v_mfma_f32_16x16x32_bf16 v[14:17], v[178:181], v[222:225], 0
	v_mfma_f32_16x16x32_bf16 v[10:13], v[186:189], v[222:225], 0
	v_mfma_f32_16x16x32_bf16 v[6:9], v[178:181], v[230:233], 0
	v_mfma_f32_16x16x32_bf16 v[2:5], v[186:189], v[230:233], 0
	v_mfma_f32_16x16x32_bf16 v[94:97], v[146:149], v[210:213], v[94:97]
	v_mfma_f32_16x16x32_bf16 v[90:93], v[154:157], v[210:213], v[90:93]
	v_mfma_f32_16x16x32_bf16 v[86:89], v[146:149], v[218:221], v[86:89]
	v_mfma_f32_16x16x32_bf16 v[82:85], v[154:157], v[218:221], v[82:85]
	v_mfma_f32_16x16x32_bf16 v[78:81], v[146:149], v[226:229], v[78:81]
	v_mfma_f32_16x16x32_bf16 v[74:77], v[154:157], v[226:229], v[74:77]
	v_mfma_f32_16x16x32_bf16 v[70:73], v[146:149], v[234:237], v[70:73]
	v_mfma_f32_16x16x32_bf16 v[66:69], v[154:157], v[234:237], v[66:69]
	v_mfma_f32_16x16x32_bf16 v[30:33], v[182:185], v[210:213], v[30:33]
	v_mfma_f32_16x16x32_bf16 v[26:29], v[202:205], v[210:213], v[26:29]
	v_mfma_f32_16x16x32_bf16 v[22:25], v[182:185], v[218:221], v[22:25]
	v_mfma_f32_16x16x32_bf16 v[18:21], v[202:205], v[218:221], v[18:21]
	v_mfma_f32_16x16x32_bf16 v[14:17], v[182:185], v[226:229], v[14:17]
	v_mfma_f32_16x16x32_bf16 v[10:13], v[202:205], v[226:229], v[10:13]
	v_mfma_f32_16x16x32_bf16 v[6:9], v[182:185], v[234:237], v[6:9]
	v_mfma_f32_16x16x32_bf16 v[2:5], v[202:205], v[234:237], v[2:5]
	s_setprio 0
	s_barrier
	s_add_i32 s22, 0, 0x18000
	s_add_i32 s23, 0, 0x1c000
	v_add_u32_e32 v154, s22, v159
	v_add_u32_e32 v202, s23, v159
	ds_read_b128 v[142:145], v154
	ds_read_b128 v[146:149], v154 offset:1024
	ds_read_b128 v[150:153], v154 offset:2048
	ds_read_b128 v[154:157], v154 offset:3072
	ds_read_b128 v[178:181], v202
	ds_read_b128 v[182:185], v202 offset:1024
	ds_read_b128 v[186:189], v202 offset:2048
	ds_read_b128 v[202:205], v202 offset:3072
	s_add_u32 s14, s14, 0x40000
	s_addc_u32 s15, s15, 0
	s_mov_b32 m0, s40
	v_lshl_add_u64 v[242:243], s[14:15], 0, v[134:135]
	ds_read_b128 v[206:209], v161 offset:32768
	ds_read_b128 v[210:213], v161 offset:33792
	ds_read_b128 v[214:217], v161 offset:34816
	ds_read_b128 v[218:221], v161 offset:35840
	ds_read_b128 v[222:225], v161 offset:36864
	ds_read_b128 v[226:229], v161 offset:37888
	ds_read_b128 v[230:233], v161 offset:38912
	ds_read_b128 v[234:237], v161 offset:39936
	global_load_lds_dwordx4 v[242:243], off
	v_lshl_add_u64 v[242:243], s[14:15], 0, v[132:133]
	s_mov_b32 m0, s41
	s_nop 0
	global_load_lds_dwordx4 v[242:243], off
	s_waitcnt vmcnt(8)
	s_waitcnt lgkmcnt(0)
	s_barrier
	s_setprio 1
	s_waitcnt lgkmcnt(0)
	v_mfma_f32_16x16x32_bf16 v[126:129], v[142:145], v[206:209], v[126:129]
	v_mfma_f32_16x16x32_bf16 v[122:125], v[150:153], v[206:209], v[122:125]
	v_mfma_f32_16x16x32_bf16 v[118:121], v[142:145], v[214:217], v[118:121]
	v_mfma_f32_16x16x32_bf16 v[114:117], v[150:153], v[214:217], v[114:117]
	v_mfma_f32_16x16x32_bf16 v[110:113], v[142:145], v[222:225], v[110:113]
	v_mfma_f32_16x16x32_bf16 v[106:109], v[150:153], v[222:225], v[106:109]
	v_mfma_f32_16x16x32_bf16 v[102:105], v[142:145], v[230:233], v[102:105]
	v_mfma_f32_16x16x32_bf16 v[98:101], v[150:153], v[230:233], v[98:101]
	v_mfma_f32_16x16x32_bf16 v[62:65], v[178:181], v[206:209], v[62:65]
	v_mfma_f32_16x16x32_bf16 v[58:61], v[186:189], v[206:209], v[58:61]
	v_mfma_f32_16x16x32_bf16 v[54:57], v[178:181], v[214:217], v[54:57]
	v_mfma_f32_16x16x32_bf16 v[50:53], v[186:189], v[214:217], v[50:53]
	v_mfma_f32_16x16x32_bf16 v[46:49], v[178:181], v[222:225], v[46:49]
	v_mfma_f32_16x16x32_bf16 v[42:45], v[186:189], v[222:225], v[42:45]
	v_mfma_f32_16x16x32_bf16 v[38:41], v[178:181], v[230:233], v[38:41]
	v_mfma_f32_16x16x32_bf16 v[34:37], v[186:189], v[230:233], v[34:37]
	v_mfma_f32_16x16x32_bf16 v[126:129], v[146:149], v[210:213], v[126:129]
	v_mfma_f32_16x16x32_bf16 v[122:125], v[154:157], v[210:213], v[122:125]
	v_mfma_f32_16x16x32_bf16 v[118:121], v[146:149], v[218:221], v[118:121]
	v_mfma_f32_16x16x32_bf16 v[114:117], v[154:157], v[218:221], v[114:117]
	v_mfma_f32_16x16x32_bf16 v[110:113], v[146:149], v[226:229], v[110:113]
	v_mfma_f32_16x16x32_bf16 v[106:109], v[154:157], v[226:229], v[106:109]
	v_mfma_f32_16x16x32_bf16 v[102:105], v[146:149], v[234:237], v[102:105]
	v_mfma_f32_16x16x32_bf16 v[98:101], v[154:157], v[234:237], v[98:101]
	v_mfma_f32_16x16x32_bf16 v[62:65], v[182:185], v[210:213], v[62:65]
	v_mfma_f32_16x16x32_bf16 v[58:61], v[202:205], v[210:213], v[58:61]
	v_mfma_f32_16x16x32_bf16 v[54:57], v[182:185], v[218:221], v[54:57]
	v_mfma_f32_16x16x32_bf16 v[50:53], v[202:205], v[218:221], v[50:53]
	v_mfma_f32_16x16x32_bf16 v[46:49], v[182:185], v[226:229], v[46:49]
	v_mfma_f32_16x16x32_bf16 v[42:45], v[202:205], v[226:229], v[42:45]
	v_mfma_f32_16x16x32_bf16 v[38:41], v[182:185], v[234:237], v[38:41]
	v_mfma_f32_16x16x32_bf16 v[34:37], v[202:205], v[234:237], v[34:37]
	s_setprio 0
	s_barrier
; #define PG8_STAGE(bufoff, gbase, voff) do { _Pragma("unroll") for (int _i = 0; _i < 2; ++_i) \
;         __builtin_amdgcn_global_load_lds((const unsigned*)((const char*)(gbase) + (voff)[_i]), (PG8_LAS unsigned*)(lds + (bufoff) + ldsw + _i * 8192), 16, 0, 0); } while (0)
; #define PG8_LDA(dst, b, h) do { _Pragma("unroll") for (int m = 0; m < 4; ++m) _Pragma("unroll") for (int k = 0; k < 2; ++k) dst[m][k] = *(const PG8_LAS bf16x8*)(lds + PG8_SA(b, h) + aoff + m * 2048 + k * 1024); } while (0)
; #define PG8_MMA_NP(ai, bj, At, Bt) do { _Pragma("unroll") for (int m = 0; m < 4; ++m) _Pragma("unroll") for (int n = 0; n < 2; ++n) _Pragma("unroll") for (int k = 0; k < 2; ++k) \
;         acc[ai][bj][m][n] = __builtin_amdgcn_mfma_f32_16x16x32_bf16(Bt[n][k], At[m][k], acc[ai][bj][m][n], 0, 0, 0); } while (0)
; #define PG8_WAIT_V(n) asm volatile("s_waitcnt vmcnt(" #n ")" ::: "memory")
; #define PG8_WAIT_L(n) asm volatile("s_waitcnt lgkmcnt(" #n ")" ::: "memory")
; #define PG8_BAR __builtin_amdgcn_s_barrier()
; #define PG8_SCHED __builtin_amdgcn_sched_barrier(0)
; template <class Epi, class Sched, bool ALIGN_EPI = false, bool SP2 = false>
; __device__ __forceinline__ void gemm_phase(PG8_LAS unsigned char* lds, const Gemm g, const Sched& S, const Epi& E) {
;     ...
;         for (int t = 0; t < nt; t += 2) {
;     ...
;             PG8_LDA(At, 1, 1); PG8_STAGE(PG8_SB(1, 0), b3, voffB); PG8_STAGE(PG8_SB(1, 1), b3 + hstep, voffB); PG8_STAGE(PG8_SA(1, 0), a3, voffA);
;             PG8_WAIT_V(8); PG8_WAIT_L(0); PG8_BAR; __builtin_amdgcn_s_setprio(1); PG8_MMA_NP(1, 0, At, B0); PG8_MMA_NP(1, 1, At, B1); __builtin_amdgcn_s_setprio(0); PG8_BAR; PG8_SCHED;
	s_add_i32 s14, s22, s8
	v_lshl_add_u64 v[162:163], v[162:163], 0, s[20:21]
	s_mov_b32 m0, s14
	ds_read_b128 v[206:209], v161 offset:49152
	ds_read_b128 v[210:213], v161 offset:50176
	ds_read_b128 v[214:217], v161 offset:51200
	ds_read_b128 v[218:221], v161 offset:52224
	ds_read_b128 v[222:225], v161 offset:53248
	ds_read_b128 v[226:229], v161 offset:54272
	ds_read_b128 v[230:233], v161 offset:55296
	ds_read_b128 v[234:237], v161 offset:56320
	global_load_lds_dwordx4 v[162:163], off
	s_add_i32 m0, s14, 0x2000
	s_add_u32 s12, s12, 0x40080
	v_lshl_add_u64 v[162:163], v[190:191], 0, s[20:21]
	s_addc_u32 s13, s13, 0
	s_add_i32 s14, s23, s8
	global_load_lds_dwordx4 v[162:163], off
	v_lshl_add_u64 v[162:163], s[12:13], 0, v[0:1]
	s_mov_b32 m0, s14
	s_nop 0
	global_load_lds_dwordx4 v[162:163], off
	v_lshl_add_u64 v[162:163], s[12:13], 0, v[130:131]
	s_add_i32 m0, s14, 0x2000
	s_nop 0
	global_load_lds_dwordx4 v[162:163], off
	v_lshl_add_u64 v[162:163], v[238:239], 0, s[20:21]
	s_mov_b32 m0, s54
	s_nop 0
	global_load_lds_dwordx4 v[162:163], off
	v_lshl_add_u64 v[162:163], v[240:241], 0, s[20:21]
	s_mov_b32 m0, s55
	s_nop 0
	global_load_lds_dwordx4 v[162:163], off
	s_waitcnt vmcnt(8)
	s_waitcnt lgkmcnt(0)
	s_barrier
	s_setprio 1
	s_waitcnt lgkmcnt(0)
	v_mfma_f32_16x16x32_bf16 v[94:97], v[142:145], v[206:209], v[94:97]
	v_mfma_f32_16x16x32_bf16 v[90:93], v[150:153], v[206:209], v[90:93]
	v_mfma_f32_16x16x32_bf16 v[86:89], v[142:145], v[214:217], v[86:89]
	v_mfma_f32_16x16x32_bf16 v[82:85], v[150:153], v[214:217], v[82:85]
	v_mfma_f32_16x16x32_bf16 v[78:81], v[142:145], v[222:225], v[78:81]
	v_mfma_f32_16x16x32_bf16 v[74:77], v[150:153], v[222:225], v[74:77]
	v_mfma_f32_16x16x32_bf16 v[70:73], v[142:145], v[230:233], v[70:73]
	v_mfma_f32_16x16x32_bf16 v[66:69], v[150:153], v[230:233], v[66:69]
	v_mfma_f32_16x16x32_bf16 v[30:33], v[178:181], v[206:209], v[30:33]
	v_mfma_f32_16x16x32_bf16 v[26:29], v[186:189], v[206:209], v[26:29]
	v_mfma_f32_16x16x32_bf16 v[22:25], v[178:181], v[214:217], v[22:25]
	v_mfma_f32_16x16x32_bf16 v[18:21], v[186:189], v[214:217], v[18:21]
	v_mfma_f32_16x16x32_bf16 v[14:17], v[178:181], v[222:225], v[14:17]
	v_mfma_f32_16x16x32_bf16 v[10:13], v[186:189], v[222:225], v[10:13]
	v_mfma_f32_16x16x32_bf16 v[6:9], v[178:181], v[230:233], v[6:9]
	v_mfma_f32_16x16x32_bf16 v[2:5], v[186:189], v[230:233], v[2:5]
	v_mfma_f32_16x16x32_bf16 v[94:97], v[146:149], v[210:213], v[94:97]
	v_mfma_f32_16x16x32_bf16 v[90:93], v[154:157], v[210:213], v[90:93]
	v_mfma_f32_16x16x32_bf16 v[86:89], v[146:149], v[218:221], v[86:89]
	v_mfma_f32_16x16x32_bf16 v[82:85], v[154:157], v[218:221], v[82:85]
	v_mfma_f32_16x16x32_bf16 v[78:81], v[146:149], v[226:229], v[78:81]
	v_mfma_f32_16x16x32_bf16 v[74:77], v[154:157], v[226:229], v[74:77]
	v_mfma_f32_16x16x32_bf16 v[70:73], v[146:149], v[234:237], v[70:73]
	v_mfma_f32_16x16x32_bf16 v[66:69], v[154:157], v[234:237], v[66:69]
	v_mfma_f32_16x16x32_bf16 v[30:33], v[182:185], v[210:213], v[30:33]
	v_mfma_f32_16x16x32_bf16 v[26:29], v[202:205], v[210:213], v[26:29]
	v_mfma_f32_16x16x32_bf16 v[22:25], v[182:185], v[218:221], v[22:25]
	v_mfma_f32_16x16x32_bf16 v[18:21], v[202:205], v[218:221], v[18:21]
	v_mfma_f32_16x16x32_bf16 v[14:17], v[182:185], v[226:229], v[14:17]
	v_mfma_f32_16x16x32_bf16 v[10:13], v[202:205], v[226:229], v[10:13]
	v_mfma_f32_16x16x32_bf16 v[6:9], v[182:185], v[234:237], v[6:9]
	v_mfma_f32_16x16x32_bf16 v[2:5], v[202:205], v[234:237], v[2:5]
	s_setprio 0
	s_barrier
	s_add_i32 s63, s63, 2
	s_add_u32 s2, s2, 0x100
	s_addc_u32 s3, s3, 0
	s_add_u32 s61, s61, 0x100
	s_addc_u32 s62, s62, 0
	s_cmp_gt_u32 s63, 13
	s_cbranch_scc0 .LBB0_432
	s_branch .Lkexit_3
	.p2align 3
	s_nop 0

; #define PG8_STAGE(bufoff, gbase, voff) do { _Pragma("unroll") for (int _i = 0; _i < 2; ++_i) \
;         __builtin_amdgcn_global_load_lds((const unsigned*)((const char*)(gbase) + (voff)[_i]), (PG8_LAS unsigned*)(lds + (bufoff) + ldsw + _i * 8192), 16, 0, 0); } while (0)
; #define PG8_LDA(dst, b, h) do { _Pragma("unroll") for (int m = 0; m < 4; ++m) _Pragma("unroll") for (int k = 0; k < 2; ++k) dst[m][k] = *(const PG8_LAS bf16x8*)(lds + PG8_SA(b, h) + aoff + m * 2048 + k * 1024); } while (0)
; #define PG8_LDB(dst, b, h) do { _Pragma("unroll") for (int n = 0; n < 2; ++n) _Pragma("unroll") for (int k = 0; k < 2; ++k) dst[n][k] = *(const PG8_LAS bf16x8*)(lds + PG8_SB(b, h) + boff + n * 2048 + k * 1024); } while (0)
; #define PG8_MMA_NP(ai, bj, At, Bt) do { _Pragma("unroll") for (int m = 0; m < 4; ++m) _Pragma("unroll") for (int n = 0; n < 2; ++n) _Pragma("unroll") for (int k = 0; k < 2; ++k) \
;         acc[ai][bj][m][n] = __builtin_amdgcn_mfma_f32_16x16x32_bf16(Bt[n][k], At[m][k], acc[ai][bj][m][n], 0, 0, 0); } while (0)
; template <class Epi, class Sched, bool ALIGN_EPI = false, bool SP2 = false>
; __device__ __forceinline__ void gemm_phase(PG8_LAS unsigned char* lds, const Gemm g, const Sched& S, const Epi& E) {
;     ...
;         const bool has_next = S.next(ui + 1, nxt);
;         const char* nA = has_next ? (const char*)g.A + (size_t)nxt.pm * tstep : cA; const char* nB = has_next ? (const char*)g.Bt + (size_t)nxt.pn * tstep : cB;
;         for (int t = 0; t < nt; t += 2) {
;             const bool last = (t == nt - 2);
;             const char* a1 = cA + (size_t)(t + 1) * kstep;
;             const char* a2 = last ? nA : cA + (size_t)(t + 2) * kstep; const char* b2 = last ? nB : cB + (size_t)(t + 2) * kstep;
;             const char* a3 = a2 + kstep; const char* b3 = b2 + kstep;
;             if (last && has_next) S.a_ready(nxt);
;             if constexpr (SP2) {
;             PG8_LDB(B0, 0, 0); PG8_LDB(B1, 0, 1); PG8_SCHED; PG8_LDA(At, 0, 0); PG8_STAGE(PG8_SA(1, 1), a1 + hstep, voffA);
;             PG8_WAIT_V(8); PG8_WAIT_L(0); PG8_BAR; __builtin_amdgcn_s_setprio(1); PG8_MMA_NP(0, 0, At, B0); PG8_MMA_NP(0, 1, At, B1); __builtin_amdgcn_s_setprio(0); PG8_BAR; PG8_SCHED;
;             PG8_LDA(At, 0, 1); PG8_STAGE(PG8_SB(0, 0), b2, voffB); PG8_STAGE(PG8_SB(0, 1), b2 + hstep, voffB); PG8_STAGE(PG8_SA(0, 0), a2, voffA);
.LBB0_1015:
	s_ashr_i32 s51, s50, 31
	s_lshl_b64 s[14:15], s[50:51], 19
	s_add_u32 s52, s90, s14
	s_addc_u32 s53, s91, s15
	s_and_b64 s[14:15], s[44:45], exec
	s_cselect_b32 s29, s53, s13
	s_cselect_b32 s30, s52, s12
	s_ashr_i32 s49, s48, 31
	s_lshl_b64 s[14:15], s[48:49], 19
	s_add_u32 s54, s31, s14
	s_addc_u32 s55, s40, s15
	s_and_b64 s[14:15], s[44:45], exec
	s_cselect_b32 s49, s55, s39
	s_cselect_b32 s51, s54, s38
	s_add_u32 s12, s12, 0x40080
	s_addc_u32 s13, s13, 0
	s_add_u32 s64, s38, 0x100
	s_addc_u32 s65, s39, 0
	s_mov_b32 s66, -2
	s_waitcnt lgkmcnt(0)
	s_add_u32 s14, s12, 0xfffc0080
	s_addc_u32 s15, s13, -1
	s_add_i32 s22, 0, 0x10000
	s_cmp_eq_u32 s66, 12
	s_cselect_b32 s39, s29, s15
	s_cselect_b32 s38, s30, s14
	v_add_u32_e32 v144, s22, v147
	s_cselect_b32 s15, s49, s65
	s_cselect_b32 s14, s51, s64
	s_add_i32 s67, 0, 0x14000
	ds_read_b128 v[140:143], v144
	ds_read_b128 v[150:153], v144 offset:1024
	ds_read_b128 v[154:157], v144 offset:2048
	ds_read_b128 v[158:161], v144 offset:3072
	v_add_u32_e32 v144, s67, v147
	ds_read_b128 v[178:181], v144
	ds_read_b128 v[182:185], v144 offset:1024
	ds_read_b128 v[186:189], v144 offset:2048
	ds_read_b128 v[202:205], v144 offset:3072
	v_lshl_add_u64 v[144:145], s[12:13], 0, v[136:137]
	s_add_i32 m0, s56, 0xc000
	ds_read_b128 v[206:209], v149
	ds_read_b128 v[210:213], v149 offset:1024
	ds_read_b128 v[214:217], v149 offset:2048
	ds_read_b128 v[218:221], v149 offset:3072
	ds_read_b128 v[222:225], v149 offset:4096
	ds_read_b128 v[226:229], v149 offset:5120
	ds_read_b128 v[230:233], v149 offset:6144
	ds_read_b128 v[234:237], v149 offset:7168
	global_load_lds_dwordx4 v[144:145], off
	v_lshl_add_u64 v[144:145], s[12:13], 0, v[138:139]
	s_add_i32 m0, s56, 0xe000
	s_nop 0
	global_load_lds_dwordx4 v[144:145], off
	s_waitcnt vmcnt(8)
	s_waitcnt lgkmcnt(0)
	s_barrier
	s_setprio 1
	s_waitcnt lgkmcnt(0)
	v_mfma_f32_16x16x32_bf16 v[126:129], v[140:143], v[206:209], 0
	v_mfma_f32_16x16x32_bf16 v[122:125], v[154:157], v[206:209], 0
	v_mfma_f32_16x16x32_bf16 v[110:113], v[140:143], v[214:217], 0
	v_mfma_f32_16x16x32_bf16 v[106:109], v[154:157], v[214:217], 0
	v_mfma_f32_16x16x32_bf16 v[94:97], v[140:143], v[222:225], 0
	v_mfma_f32_16x16x32_bf16 v[90:93], v[154:157], v[222:225], 0
	v_mfma_f32_16x16x32_bf16 v[78:81], v[140:143], v[230:233], 0
	v_mfma_f32_16x16x32_bf16 v[74:77], v[154:157], v[230:233], 0
	v_mfma_f32_16x16x32_bf16 v[118:121], v[178:181], v[206:209], 0
	v_mfma_f32_16x16x32_bf16 v[114:117], v[186:189], v[206:209], 0
	v_mfma_f32_16x16x32_bf16 v[102:105], v[178:181], v[214:217], 0
	v_mfma_f32_16x16x32_bf16 v[98:101], v[186:189], v[214:217], 0
	v_mfma_f32_16x16x32_bf16 v[86:89], v[178:181], v[222:225], 0
	v_mfma_f32_16x16x32_bf16 v[82:85], v[186:189], v[222:225], 0
	v_mfma_f32_16x16x32_bf16 v[70:73], v[178:181], v[230:233], 0
	v_mfma_f32_16x16x32_bf16 v[66:69], v[186:189], v[230:233], 0
	v_mfma_f32_16x16x32_bf16 v[126:129], v[150:153], v[210:213], v[126:129]
	v_mfma_f32_16x16x32_bf16 v[122:125], v[158:161], v[210:213], v[122:125]
	v_mfma_f32_16x16x32_bf16 v[110:113], v[150:153], v[218:221], v[110:113]
	v_mfma_f32_16x16x32_bf16 v[106:109], v[158:161], v[218:221], v[106:109]
	v_mfma_f32_16x16x32_bf16 v[94:97], v[150:153], v[226:229], v[94:97]
	v_mfma_f32_16x16x32_bf16 v[90:93], v[158:161], v[226:229], v[90:93]
	v_mfma_f32_16x16x32_bf16 v[78:81], v[150:153], v[234:237], v[78:81]
	v_mfma_f32_16x16x32_bf16 v[74:77], v[158:161], v[234:237], v[74:77]
	v_mfma_f32_16x16x32_bf16 v[118:121], v[182:185], v[210:213], v[118:121]
	v_mfma_f32_16x16x32_bf16 v[114:117], v[202:205], v[210:213], v[114:117]
	v_mfma_f32_16x16x32_bf16 v[102:105], v[182:185], v[218:221], v[102:105]
	v_mfma_f32_16x16x32_bf16 v[98:101], v[202:205], v[218:221], v[98:101]
	v_mfma_f32_16x16x32_bf16 v[86:89], v[182:185], v[226:229], v[86:89]
	v_mfma_f32_16x16x32_bf16 v[82:85], v[202:205], v[226:229], v[82:85]
	v_mfma_f32_16x16x32_bf16 v[70:73], v[182:185], v[234:237], v[70:73]
	v_mfma_f32_16x16x32_bf16 v[66:69], v[202:205], v[234:237], v[66:69]
	s_setprio 0
	s_barrier
	s_add_i32 s22, s22, s41
	v_lshl_add_u64 v[144:145], s[14:15], 0, v[0:1]
	s_mov_b32 m0, s22
	ds_read_b128 v[206:209], v149 offset:16384
	ds_read_b128 v[210:213], v149 offset:17408
	ds_read_b128 v[214:217], v149 offset:18432
	ds_read_b128 v[218:221], v149 offset:19456
	ds_read_b128 v[222:225], v149 offset:20480
	ds_read_b128 v[226:229], v149 offset:21504
	ds_read_b128 v[230:233], v149 offset:22528
	ds_read_b128 v[234:237], v149 offset:23552
	global_load_lds_dwordx4 v[144:145], off
	s_add_i32 m0, s22, 0x2000
	s_add_u32 s22, s14, 0x40000
	v_lshl_add_u64 v[162:163], s[14:15], 0, v[130:131]
	s_addc_u32 s23, s15, 0
	s_add_i32 s67, s67, s41
	global_load_lds_dwordx4 v[162:163], off
	v_lshl_add_u64 v[190:191], s[22:23], 0, v[0:1]
	s_mov_b32 m0, s67
	v_lshl_add_u64 v[238:239], s[38:39], 0, v[132:133]
	global_load_lds_dwordx4 v[190:191], off
	v_lshl_add_u64 v[190:191], s[22:23], 0, v[130:131]
	s_add_i32 m0, s67, 0x2000
	s_nop 0
	global_load_lds_dwordx4 v[190:191], off
	v_lshl_add_u64 v[190:191], s[38:39], 0, v[134:135]
	s_mov_b32 m0, s56
	s_nop 0
	global_load_lds_dwordx4 v[190:191], off
	s_mov_b32 m0, s57
	s_nop 0
	global_load_lds_dwordx4 v[238:239], off
	s_waitcnt vmcnt(8)
	s_waitcnt lgkmcnt(0)
	s_barrier
; #define PG8_STAGE(bufoff, gbase, voff) do { _Pragma("unroll") for (int _i = 0; _i < 2; ++_i) \
;         __builtin_amdgcn_global_load_lds((const unsigned*)((const char*)(gbase) + (voff)[_i]), (PG8_LAS unsigned*)(lds + (bufoff) + ldsw + _i * 8192), 16, 0, 0); } while (0)
; #define PG8_LDA(dst, b, h) do { _Pragma("unroll") for (int m = 0; m < 4; ++m) _Pragma("unroll") for (int k = 0; k < 2; ++k) dst[m][k] = *(const PG8_LAS bf16x8*)(lds + PG8_SA(b, h) + aoff + m * 2048 + k * 1024); } while (0)
; #define PG8_LDB(dst, b, h) do { _Pragma("unroll") for (int n = 0; n < 2; ++n) _Pragma("unroll") for (int k = 0; k < 2; ++k) dst[n][k] = *(const PG8_LAS bf16x8*)(lds + PG8_SB(b, h) + boff + n * 2048 + k * 1024); } while (0)
; #define PG8_MMA_NP(ai, bj, At, Bt) do { _Pragma("unroll") for (int m = 0; m < 4; ++m) _Pragma("unroll") for (int n = 0; n < 2; ++n) _Pragma("unroll") for (int k = 0; k < 2; ++k) \
;         acc[ai][bj][m][n] = __builtin_amdgcn_mfma_f32_16x16x32_bf16(Bt[n][k], At[m][k], acc[ai][bj][m][n], 0, 0, 0); } while (0)
; #define PG8_WAIT_V(n) asm volatile("s_waitcnt vmcnt(" #n ")" ::: "memory")
; #define PG8_WAIT_L(n) asm volatile("s_waitcnt lgkmcnt(" #n ")" ::: "memory")
; #define PG8_BAR __builtin_amdgcn_s_barrier()
; #define PG8_SCHED __builtin_amdgcn_sched_barrier(0)
; template <class Epi, class Sched, bool ALIGN_EPI = false, bool SP2 = false>
; __device__ __forceinline__ void gemm_phase(PG8_LAS unsigned char* lds, const Gemm g, const Sched& S, const Epi& E) {
;     ...
;             PG8_WAIT_V(8); PG8_WAIT_L(0); PG8_BAR; __builtin_amdgcn_s_setprio(1); PG8_MMA_NP(1, 0, At, B0); PG8_MMA_NP(1, 1, At, B1); __builtin_amdgcn_s_setprio(0); PG8_BAR; PG8_SCHED;
;             PG8_LDB(B0, 1, 0); PG8_LDB(B1, 1, 1); PG8_SCHED; PG8_LDA(At, 1, 0); PG8_STAGE(PG8_SA(0, 1), a2 + hstep, voffA);
;             PG8_WAIT_V(8); PG8_WAIT_L(0); PG8_BAR; __builtin_amdgcn_s_setprio(1); PG8_MMA_NP(0, 0, At, B0); PG8_MMA_NP(0, 1, At, B1); __builtin_amdgcn_s_setprio(0); PG8_BAR; PG8_SCHED;
	s_setprio 1
	s_waitcnt lgkmcnt(0)
	v_mfma_f32_16x16x32_bf16 v[62:65], v[140:143], v[206:209], 0
	v_mfma_f32_16x16x32_bf16 v[58:61], v[154:157], v[206:209], 0
	v_mfma_f32_16x16x32_bf16 v[46:49], v[140:143], v[214:217], 0
	v_mfma_f32_16x16x32_bf16 v[42:45], v[154:157], v[214:217], 0
	v_mfma_f32_16x16x32_bf16 v[30:33], v[140:143], v[222:225], 0
	v_mfma_f32_16x16x32_bf16 v[26:29], v[154:157], v[222:225], 0
	v_mfma_f32_16x16x32_bf16 v[14:17], v[140:143], v[230:233], 0
	v_mfma_f32_16x16x32_bf16 v[10:13], v[154:157], v[230:233], 0
	v_mfma_f32_16x16x32_bf16 v[54:57], v[178:181], v[206:209], 0
	v_mfma_f32_16x16x32_bf16 v[50:53], v[186:189], v[206:209], 0
	v_mfma_f32_16x16x32_bf16 v[38:41], v[178:181], v[214:217], 0
	v_mfma_f32_16x16x32_bf16 v[34:37], v[186:189], v[214:217], 0
	v_mfma_f32_16x16x32_bf16 v[22:25], v[178:181], v[222:225], 0
	v_mfma_f32_16x16x32_bf16 v[18:21], v[186:189], v[222:225], 0
	v_mfma_f32_16x16x32_bf16 v[6:9], v[178:181], v[230:233], 0
	v_mfma_f32_16x16x32_bf16 v[2:5], v[186:189], v[230:233], 0
	v_mfma_f32_16x16x32_bf16 v[62:65], v[150:153], v[210:213], v[62:65]
	v_mfma_f32_16x16x32_bf16 v[58:61], v[158:161], v[210:213], v[58:61]
	v_mfma_f32_16x16x32_bf16 v[46:49], v[150:153], v[218:221], v[46:49]
	v_mfma_f32_16x16x32_bf16 v[42:45], v[158:161], v[218:221], v[42:45]
	v_mfma_f32_16x16x32_bf16 v[30:33], v[150:153], v[226:229], v[30:33]
	v_mfma_f32_16x16x32_bf16 v[26:29], v[158:161], v[226:229], v[26:29]
	v_mfma_f32_16x16x32_bf16 v[14:17], v[150:153], v[234:237], v[14:17]
	v_mfma_f32_16x16x32_bf16 v[10:13], v[158:161], v[234:237], v[10:13]
	v_mfma_f32_16x16x32_bf16 v[54:57], v[182:185], v[210:213], v[54:57]
	v_mfma_f32_16x16x32_bf16 v[50:53], v[202:205], v[210:213], v[50:53]
	v_mfma_f32_16x16x32_bf16 v[38:41], v[182:185], v[218:221], v[38:41]
	v_mfma_f32_16x16x32_bf16 v[34:37], v[202:205], v[218:221], v[34:37]
	v_mfma_f32_16x16x32_bf16 v[22:25], v[182:185], v[226:229], v[22:25]
	v_mfma_f32_16x16x32_bf16 v[18:21], v[202:205], v[226:229], v[18:21]
	v_mfma_f32_16x16x32_bf16 v[6:9], v[182:185], v[234:237], v[6:9]
	v_mfma_f32_16x16x32_bf16 v[2:5], v[202:205], v[234:237], v[2:5]
	s_setprio 0
	s_barrier
	s_add_i32 s67, 0, 0x18000
	s_add_i32 s68, 0, 0x1c000
	v_add_u32_e32 v158, s67, v147
	v_add_u32_e32 v202, s68, v147
	ds_read_b128 v[140:143], v158
	ds_read_b128 v[150:153], v158 offset:1024
	ds_read_b128 v[154:157], v158 offset:2048
	ds_read_b128 v[158:161], v158 offset:3072
	ds_read_b128 v[178:181], v202
	ds_read_b128 v[182:185], v202 offset:1024
	ds_read_b128 v[186:189], v202 offset:2048
	ds_read_b128 v[202:205], v202 offset:3072
	s_add_u32 s22, s38, 0x40000
	s_addc_u32 s23, s39, 0
	s_mov_b32 m0, s58
	v_lshl_add_u64 v[240:241], s[22:23], 0, v[134:135]
	ds_read_b128 v[206:209], v149 offset:32768
	ds_read_b128 v[210:213], v149 offset:33792
	ds_read_b128 v[214:217], v149 offset:34816
	ds_read_b128 v[218:221], v149 offset:35840
	ds_read_b128 v[222:225], v149 offset:36864
	ds_read_b128 v[226:229], v149 offset:37888
	ds_read_b128 v[230:233], v149 offset:38912
	ds_read_b128 v[234:237], v149 offset:39936
	global_load_lds_dwordx4 v[240:241], off
	v_lshl_add_u64 v[240:241], s[22:23], 0, v[132:133]
	s_mov_b32 m0, s59
	s_nop 0
	global_load_lds_dwordx4 v[240:241], off
	s_waitcnt vmcnt(8)
	s_waitcnt lgkmcnt(0)
	s_barrier
	s_setprio 1
	s_waitcnt lgkmcnt(0)
	v_mfma_f32_16x16x32_bf16 v[126:129], v[140:143], v[206:209], v[126:129]
	v_mfma_f32_16x16x32_bf16 v[122:125], v[154:157], v[206:209], v[122:125]
	v_mfma_f32_16x16x32_bf16 v[110:113], v[140:143], v[214:217], v[110:113]
	v_mfma_f32_16x16x32_bf16 v[106:109], v[154:157], v[214:217], v[106:109]
	v_mfma_f32_16x16x32_bf16 v[94:97], v[140:143], v[222:225], v[94:97]
	v_mfma_f32_16x16x32_bf16 v[90:93], v[154:157], v[222:225], v[90:93]
	v_mfma_f32_16x16x32_bf16 v[78:81], v[140:143], v[230:233], v[78:81]
	v_mfma_f32_16x16x32_bf16 v[74:77], v[154:157], v[230:233], v[74:77]
	v_mfma_f32_16x16x32_bf16 v[118:121], v[178:181], v[206:209], v[118:121]
	v_mfma_f32_16x16x32_bf16 v[114:117], v[186:189], v[206:209], v[114:117]
	v_mfma_f32_16x16x32_bf16 v[102:105], v[178:181], v[214:217], v[102:105]
	v_mfma_f32_16x16x32_bf16 v[98:101], v[186:189], v[214:217], v[98:101]
	v_mfma_f32_16x16x32_bf16 v[86:89], v[178:181], v[222:225], v[86:89]
	v_mfma_f32_16x16x32_bf16 v[82:85], v[186:189], v[222:225], v[82:85]
	v_mfma_f32_16x16x32_bf16 v[70:73], v[178:181], v[230:233], v[70:73]
	v_mfma_f32_16x16x32_bf16 v[66:69], v[186:189], v[230:233], v[66:69]
	v_mfma_f32_16x16x32_bf16 v[126:129], v[150:153], v[210:213], v[126:129]
	v_mfma_f32_16x16x32_bf16 v[122:125], v[158:161], v[210:213], v[122:125]
	v_mfma_f32_16x16x32_bf16 v[110:113], v[150:153], v[218:221], v[110:113]
	v_mfma_f32_16x16x32_bf16 v[106:109], v[158:161], v[218:221], v[106:109]
	v_mfma_f32_16x16x32_bf16 v[94:97], v[150:153], v[226:229], v[94:97]
	v_mfma_f32_16x16x32_bf16 v[90:93], v[158:161], v[226:229], v[90:93]
	v_mfma_f32_16x16x32_bf16 v[78:81], v[150:153], v[234:237], v[78:81]
	v_mfma_f32_16x16x32_bf16 v[74:77], v[158:161], v[234:237], v[74:77]
	v_mfma_f32_16x16x32_bf16 v[118:121], v[182:185], v[210:213], v[118:121]
	v_mfma_f32_16x16x32_bf16 v[114:117], v[202:205], v[210:213], v[114:117]
	v_mfma_f32_16x16x32_bf16 v[102:105], v[182:185], v[218:221], v[102:105]
	v_mfma_f32_16x16x32_bf16 v[98:101], v[202:205], v[218:221], v[98:101]
	v_mfma_f32_16x16x32_bf16 v[86:89], v[182:185], v[226:229], v[86:89]
	v_mfma_f32_16x16x32_bf16 v[82:85], v[202:205], v[226:229], v[82:85]
	v_mfma_f32_16x16x32_bf16 v[70:73], v[182:185], v[234:237], v[70:73]
	v_mfma_f32_16x16x32_bf16 v[66:69], v[202:205], v[234:237], v[66:69]
	s_setprio 0
	s_barrier
; #define PG8_STAGE(bufoff, gbase, voff) do { _Pragma("unroll") for (int _i = 0; _i < 2; ++_i) \
;         __builtin_amdgcn_global_load_lds((const unsigned*)((const char*)(gbase) + (voff)[_i]), (PG8_LAS unsigned*)(lds + (bufoff) + ldsw + _i * 8192), 16, 0, 0); } while (0)
; #define PG8_LDA(dst, b, h) do { _Pragma("unroll") for (int m = 0; m < 4; ++m) _Pragma("unroll") for (int k = 0; k < 2; ++k) dst[m][k] = *(const PG8_LAS bf16x8*)(lds + PG8_SA(b, h) + aoff + m * 2048 + k * 1024); } while (0)
; #define PG8_MMA_NP(ai, bj, At, Bt) do { _Pragma("unroll") for (int m = 0; m < 4; ++m) _Pragma("unroll") for (int n = 0; n < 2; ++n) _Pragma("unroll") for (int k = 0; k < 2; ++k) \
;         acc[ai][bj][m][n] = __builtin_amdgcn_mfma_f32_16x16x32_bf16(Bt[n][k], At[m][k], acc[ai][bj][m][n], 0, 0, 0); } while (0)
; #define PG8_WAIT_V(n) asm volatile("s_waitcnt vmcnt(" #n ")" ::: "memory")
; #define PG8_WAIT_L(n) asm volatile("s_waitcnt lgkmcnt(" #n ")" ::: "memory")
; #define PG8_BAR __builtin_amdgcn_s_barrier()
; #define PG8_SCHED __builtin_amdgcn_sched_barrier(0)
; template <class Epi, class Sched, bool ALIGN_EPI = false, bool SP2 = false>
; __device__ __forceinline__ void gemm_phase(PG8_LAS unsigned char* lds, const Gemm g, const Sched& S, const Epi& E) {
;     ...
;         for (int t = 0; t < nt; t += 2) {
;     ...
;             PG8_LDA(At, 1, 1); PG8_STAGE(PG8_SB(1, 0), b3, voffB); PG8_STAGE(PG8_SB(1, 1), b3 + hstep, voffB); PG8_STAGE(PG8_SA(1, 0), a3, voffA);
;             PG8_WAIT_V(8); PG8_WAIT_L(0); PG8_BAR; __builtin_amdgcn_s_setprio(1); PG8_MMA_NP(1, 0, At, B0); PG8_MMA_NP(1, 1, At, B1); __builtin_amdgcn_s_setprio(0); PG8_BAR; PG8_SCHED;
	s_add_i32 s22, s67, s41
	v_lshl_add_u64 v[144:145], v[144:145], 0, s[20:21]
	s_mov_b32 m0, s22
	ds_read_b128 v[206:209], v149 offset:49152
	ds_read_b128 v[210:213], v149 offset:50176
	ds_read_b128 v[214:217], v149 offset:51200
	ds_read_b128 v[218:221], v149 offset:52224
	ds_read_b128 v[222:225], v149 offset:53248
	ds_read_b128 v[226:229], v149 offset:54272
	ds_read_b128 v[230:233], v149 offset:55296
	ds_read_b128 v[234:237], v149 offset:56320
	global_load_lds_dwordx4 v[144:145], off
	s_add_i32 m0, s22, 0x2000
	s_add_u32 s14, s14, 0x40080
	v_lshl_add_u64 v[144:145], v[162:163], 0, s[20:21]
	s_addc_u32 s15, s15, 0
	s_add_i32 s22, s68, s41
	global_load_lds_dwordx4 v[144:145], off
	v_lshl_add_u64 v[144:145], s[14:15], 0, v[0:1]
	s_mov_b32 m0, s22
	s_nop 0
	global_load_lds_dwordx4 v[144:145], off
	v_lshl_add_u64 v[144:145], s[14:15], 0, v[130:131]
	s_add_i32 m0, s22, 0x2000
	s_nop 0
	global_load_lds_dwordx4 v[144:145], off
	v_lshl_add_u64 v[144:145], v[190:191], 0, s[20:21]
	s_mov_b32 m0, s61
	s_nop 0
	global_load_lds_dwordx4 v[144:145], off
	v_lshl_add_u64 v[144:145], v[238:239], 0, s[20:21]
	s_mov_b32 m0, s62
	s_nop 0
	global_load_lds_dwordx4 v[144:145], off
	s_waitcnt vmcnt(8)
	s_waitcnt lgkmcnt(0)
	s_barrier
	s_setprio 1
	s_waitcnt lgkmcnt(0)
	v_mfma_f32_16x16x32_bf16 v[62:65], v[140:143], v[206:209], v[62:65]
	v_mfma_f32_16x16x32_bf16 v[58:61], v[154:157], v[206:209], v[58:61]
	v_mfma_f32_16x16x32_bf16 v[46:49], v[140:143], v[214:217], v[46:49]
	v_mfma_f32_16x16x32_bf16 v[42:45], v[154:157], v[214:217], v[42:45]
	v_mfma_f32_16x16x32_bf16 v[30:33], v[140:143], v[222:225], v[30:33]
	v_mfma_f32_16x16x32_bf16 v[26:29], v[154:157], v[222:225], v[26:29]
	v_mfma_f32_16x16x32_bf16 v[14:17], v[140:143], v[230:233], v[14:17]
	v_mfma_f32_16x16x32_bf16 v[10:13], v[154:157], v[230:233], v[10:13]
	v_mfma_f32_16x16x32_bf16 v[54:57], v[178:181], v[206:209], v[54:57]
	v_mfma_f32_16x16x32_bf16 v[50:53], v[186:189], v[206:209], v[50:53]
	v_mfma_f32_16x16x32_bf16 v[38:41], v[178:181], v[214:217], v[38:41]
	v_mfma_f32_16x16x32_bf16 v[34:37], v[186:189], v[214:217], v[34:37]
	v_mfma_f32_16x16x32_bf16 v[22:25], v[178:181], v[222:225], v[22:25]
	v_mfma_f32_16x16x32_bf16 v[18:21], v[186:189], v[222:225], v[18:21]
	v_mfma_f32_16x16x32_bf16 v[6:9], v[178:181], v[230:233], v[6:9]
	v_mfma_f32_16x16x32_bf16 v[2:5], v[186:189], v[230:233], v[2:5]
	v_mfma_f32_16x16x32_bf16 v[62:65], v[150:153], v[210:213], v[62:65]
	v_mfma_f32_16x16x32_bf16 v[58:61], v[158:161], v[210:213], v[58:61]
	v_mfma_f32_16x16x32_bf16 v[46:49], v[150:153], v[218:221], v[46:49]
	v_mfma_f32_16x16x32_bf16 v[42:45], v[158:161], v[218:221], v[42:45]
	v_mfma_f32_16x16x32_bf16 v[30:33], v[150:153], v[226:229], v[30:33]
	v_mfma_f32_16x16x32_bf16 v[26:29], v[158:161], v[226:229], v[26:29]
	v_mfma_f32_16x16x32_bf16 v[14:17], v[150:153], v[234:237], v[14:17]
	v_mfma_f32_16x16x32_bf16 v[10:13], v[158:161], v[234:237], v[10:13]
	v_mfma_f32_16x16x32_bf16 v[54:57], v[182:185], v[210:213], v[54:57]
	v_mfma_f32_16x16x32_bf16 v[50:53], v[202:205], v[210:213], v[50:53]
	v_mfma_f32_16x16x32_bf16 v[38:41], v[182:185], v[218:221], v[38:41]
	v_mfma_f32_16x16x32_bf16 v[34:37], v[202:205], v[218:221], v[34:37]
	v_mfma_f32_16x16x32_bf16 v[22:25], v[182:185], v[226:229], v[22:25]
	v_mfma_f32_16x16x32_bf16 v[18:21], v[202:205], v[226:229], v[18:21]
	v_mfma_f32_16x16x32_bf16 v[6:9], v[182:185], v[234:237], v[6:9]
	v_mfma_f32_16x16x32_bf16 v[2:5], v[202:205], v[234:237], v[2:5]
	s_setprio 0
	s_barrier
	s_add_i32 s66, s66, 2
	s_add_u32 s12, s12, 0x100
	s_addc_u32 s13, s13, 0
	s_add_u32 s64, s64, 0x100
	s_addc_u32 s65, s65, 0
	s_cmp_gt_u32 s66, 13
	s_cbranch_scc0 .LBB0_1016
	s_branch .Lkexit_4
	.p2align 3
	s_nop 0

; #define PG8_STAGE(bufoff, gbase, voff) do { _Pragma("unroll") for (int _i = 0; _i < 2; ++_i) \
;         __builtin_amdgcn_global_load_lds((const unsigned*)((const char*)(gbase) + (voff)[_i]), (PG8_LAS unsigned*)(lds + (bufoff) + ldsw + _i * 8192), 16, 0, 0); } while (0)
; #define PG8_LDA(dst, b, h) do { _Pragma("unroll") for (int m = 0; m < 4; ++m) _Pragma("unroll") for (int k = 0; k < 2; ++k) dst[m][k] = *(const PG8_LAS bf16x8*)(lds + PG8_SA(b, h) + aoff + m * 2048 + k * 1024); } while (0)
; #define PG8_LDB(dst, b, h) do { _Pragma("unroll") for (int n = 0; n < 2; ++n) _Pragma("unroll") for (int k = 0; k < 2; ++k) dst[n][k] = *(const PG8_LAS bf16x8*)(lds + PG8_SB(b, h) + boff + n * 2048 + k * 1024); } while (0)
; #define PG8_MMA_NP(ai, bj, At, Bt) do { _Pragma("unroll") for (int m = 0; m < 4; ++m) _Pragma("unroll") for (int n = 0; n < 2; ++n) _Pragma("unroll") for (int k = 0; k < 2; ++k) \
;         acc[ai][bj][m][n] = __builtin_amdgcn_mfma_f32_16x16x32_bf16(Bt[n][k], At[m][k], acc[ai][bj][m][n], 0, 0, 0); } while (0)
; template <class Epi, class Sched, bool ALIGN_EPI = false, bool SP2 = false>
; __device__ __forceinline__ void gemm_phase(PG8_LAS unsigned char* lds, const Gemm g, const Sched& S, const Epi& E) {
;     ...
;         const bool has_next = S.next(ui + 1, nxt);
;         const char* nA = has_next ? (const char*)g.A + (size_t)nxt.pm * tstep : cA; const char* nB = has_next ? (const char*)g.Bt + (size_t)nxt.pn * tstep : cB;
;         for (int t = 0; t < nt; t += 2) {
;             const bool last = (t == nt - 2);
;             const char* a1 = cA + (size_t)(t + 1) * kstep;
;             const char* a2 = last ? nA : cA + (size_t)(t + 2) * kstep; const char* b2 = last ? nB : cB + (size_t)(t + 2) * kstep;
;             const char* a3 = a2 + kstep; const char* b3 = b2 + kstep;
;             if (last && has_next) S.a_ready(nxt);
;             if constexpr (SP2) {
;             PG8_LDB(B0, 0, 0); PG8_LDB(B1, 0, 1); PG8_SCHED; PG8_LDA(At, 0, 0); PG8_STAGE(PG8_SA(1, 1), a1 + hstep, voffA);
;             PG8_WAIT_V(8); PG8_WAIT_L(0); PG8_BAR; __builtin_amdgcn_s_setprio(1); PG8_MMA_NP(0, 0, At, B0); PG8_MMA_NP(0, 1, At, B1); __builtin_amdgcn_s_setprio(0); PG8_BAR; PG8_SCHED;
;             PG8_LDA(At, 0, 1); PG8_STAGE(PG8_SB(0, 0), b2, voffB); PG8_STAGE(PG8_SB(0, 1), b2 + hstep, voffB); PG8_STAGE(PG8_SA(0, 0), a2, voffA);
.LBB0_1121:
	s_ashr_i32 s49, s48, 31
	s_lshl_b64 s[14:15], s[48:49], 19
	s_add_u32 s50, s86, s14
	s_addc_u32 s51, s87, s15
	s_and_b64 s[14:15], s[38:39], exec
	s_cselect_b32 s49, s51, s3
	s_cselect_b32 s59, s50, s2
	s_ashr_i32 s47, s46, 31
	s_lshl_b64 s[14:15], s[46:47], 19
	s_add_u32 s52, s8, s14
	s_addc_u32 s53, s10, s15
	s_and_b64 s[14:15], s[38:39], exec
	s_cselect_b32 s47, s53, s13
	s_cselect_b32 s60, s52, s12
	s_add_u32 s2, s2, 0x40080
	s_addc_u32 s3, s3, 0
	s_add_u32 s61, s12, 0x100
	s_addc_u32 s62, s13, 0
	s_mov_b32 s63, -2
	s_add_u32 s12, s2, 0xfffc0080
	s_addc_u32 s13, s3, -1
	s_add_i32 s22, 0, 0x10000
	s_cmp_eq_u32 s63, 12
	s_cselect_b32 s15, s49, s13
	s_cselect_b32 s14, s59, s12
	s_cselect_b32 s13, s47, s62
	s_cselect_b32 s12, s60, s61
	s_add_i32 s64, 0, 0x14000
	v_add_u32_e32 v154, s22, v183
	v_add_u32_e32 v162, s64, v183
	ds_read_b128 v[130:133], v154
	ds_read_b128 v[146:149], v154 offset:1024
	ds_read_b128 v[150:153], v154 offset:2048
	ds_read_b128 v[154:157], v154 offset:3072
	ds_read_b128 v[158:161], v162
	ds_read_b128 v[178:181], v162 offset:1024
	ds_read_b128 v[186:189], v162 offset:2048
	ds_read_b128 v[202:205], v162 offset:3072
	v_lshl_add_u64 v[162:163], s[2:3], 0, v[142:143]
	s_add_i32 m0, s30, 0xc000
	ds_read_b128 v[206:209], v185
	ds_read_b128 v[210:213], v185 offset:1024
	ds_read_b128 v[214:217], v185 offset:2048
	ds_read_b128 v[218:221], v185 offset:3072
	ds_read_b128 v[222:225], v185 offset:4096
	ds_read_b128 v[226:229], v185 offset:5120
	ds_read_b128 v[230:233], v185 offset:6144
	ds_read_b128 v[234:237], v185 offset:7168
	global_load_lds_dwordx4 v[162:163], off
	v_lshl_add_u64 v[162:163], s[2:3], 0, v[144:145]
	s_add_i32 m0, s30, 0xe000
	s_nop 0
	global_load_lds_dwordx4 v[162:163], off
	s_waitcnt vmcnt(8)
	s_waitcnt lgkmcnt(0)
	s_barrier
	s_setprio 1
	s_waitcnt lgkmcnt(0)
	v_mfma_f32_16x16x32_bf16 v[126:129], v[130:133], v[206:209], 0
	v_mfma_f32_16x16x32_bf16 v[118:121], v[150:153], v[206:209], 0
	v_mfma_f32_16x16x32_bf16 v[110:113], v[130:133], v[214:217], 0
	v_mfma_f32_16x16x32_bf16 v[102:105], v[150:153], v[214:217], 0
	v_mfma_f32_16x16x32_bf16 v[94:97], v[130:133], v[222:225], 0
	v_mfma_f32_16x16x32_bf16 v[86:89], v[150:153], v[222:225], 0
	v_mfma_f32_16x16x32_bf16 v[78:81], v[130:133], v[230:233], 0
	v_mfma_f32_16x16x32_bf16 v[70:73], v[150:153], v[230:233], 0
	v_mfma_f32_16x16x32_bf16 v[122:125], v[158:161], v[206:209], 0
	v_mfma_f32_16x16x32_bf16 v[114:117], v[186:189], v[206:209], 0
	v_mfma_f32_16x16x32_bf16 v[106:109], v[158:161], v[214:217], 0
	v_mfma_f32_16x16x32_bf16 v[98:101], v[186:189], v[214:217], 0
	v_mfma_f32_16x16x32_bf16 v[90:93], v[158:161], v[222:225], 0
	v_mfma_f32_16x16x32_bf16 v[82:85], v[186:189], v[222:225], 0
	v_mfma_f32_16x16x32_bf16 v[74:77], v[158:161], v[230:233], 0
	v_mfma_f32_16x16x32_bf16 v[66:69], v[186:189], v[230:233], 0
	v_mfma_f32_16x16x32_bf16 v[126:129], v[146:149], v[210:213], v[126:129]
	v_mfma_f32_16x16x32_bf16 v[118:121], v[154:157], v[210:213], v[118:121]
	v_mfma_f32_16x16x32_bf16 v[110:113], v[146:149], v[218:221], v[110:113]
	v_mfma_f32_16x16x32_bf16 v[102:105], v[154:157], v[218:221], v[102:105]
	v_mfma_f32_16x16x32_bf16 v[94:97], v[146:149], v[226:229], v[94:97]
	v_mfma_f32_16x16x32_bf16 v[86:89], v[154:157], v[226:229], v[86:89]
	v_mfma_f32_16x16x32_bf16 v[78:81], v[146:149], v[234:237], v[78:81]
	v_mfma_f32_16x16x32_bf16 v[70:73], v[154:157], v[234:237], v[70:73]
	v_mfma_f32_16x16x32_bf16 v[122:125], v[178:181], v[210:213], v[122:125]
	v_mfma_f32_16x16x32_bf16 v[114:117], v[202:205], v[210:213], v[114:117]
	v_mfma_f32_16x16x32_bf16 v[106:109], v[178:181], v[218:221], v[106:109]
	v_mfma_f32_16x16x32_bf16 v[98:101], v[202:205], v[218:221], v[98:101]
	v_mfma_f32_16x16x32_bf16 v[90:93], v[178:181], v[226:229], v[90:93]
	v_mfma_f32_16x16x32_bf16 v[82:85], v[202:205], v[226:229], v[82:85]
	v_mfma_f32_16x16x32_bf16 v[74:77], v[178:181], v[234:237], v[74:77]
	v_mfma_f32_16x16x32_bf16 v[66:69], v[202:205], v[234:237], v[66:69]
	s_setprio 0
	s_barrier
	s_add_i32 s22, s22, s29
	v_lshl_add_u64 v[162:163], s[12:13], 0, v[0:1]
	s_mov_b32 m0, s22
	ds_read_b128 v[206:209], v185 offset:16384
	ds_read_b128 v[210:213], v185 offset:17408
	ds_read_b128 v[214:217], v185 offset:18432
	ds_read_b128 v[218:221], v185 offset:19456
	ds_read_b128 v[222:225], v185 offset:20480
	ds_read_b128 v[226:229], v185 offset:21504
	ds_read_b128 v[230:233], v185 offset:22528
	ds_read_b128 v[234:237], v185 offset:23552
	global_load_lds_dwordx4 v[162:163], off
	s_add_i32 m0, s22, 0x2000
	s_add_u32 s22, s12, 0x40000
	v_lshl_add_u64 v[190:191], s[12:13], 0, v[134:135]
	s_addc_u32 s23, s13, 0
	s_add_i32 s64, s64, s29
	global_load_lds_dwordx4 v[190:191], off
	v_lshl_add_u64 v[238:239], s[22:23], 0, v[0:1]
	s_mov_b32 m0, s64
	v_lshl_add_u64 v[240:241], s[14:15], 0, v[136:137]
	global_load_lds_dwordx4 v[238:239], off
	v_lshl_add_u64 v[238:239], s[22:23], 0, v[134:135]
	s_add_i32 m0, s64, 0x2000
	s_nop 0
	global_load_lds_dwordx4 v[238:239], off
	v_lshl_add_u64 v[238:239], s[14:15], 0, v[138:139]
	s_mov_b32 m0, s30
	s_nop 0
	global_load_lds_dwordx4 v[238:239], off
	s_mov_b32 m0, s31
	s_nop 0
	global_load_lds_dwordx4 v[240:241], off
	s_waitcnt vmcnt(8)
	s_waitcnt lgkmcnt(0)
	s_barrier
; #define PG8_STAGE(bufoff, gbase, voff) do { _Pragma("unroll") for (int _i = 0; _i < 2; ++_i) \
;         __builtin_amdgcn_global_load_lds((const unsigned*)((const char*)(gbase) + (voff)[_i]), (PG8_LAS unsigned*)(lds + (bufoff) + ldsw + _i * 8192), 16, 0, 0); } while (0)
; #define PG8_LDA(dst, b, h) do { _Pragma("unroll") for (int m = 0; m < 4; ++m) _Pragma("unroll") for (int k = 0; k < 2; ++k) dst[m][k] = *(const PG8_LAS bf16x8*)(lds + PG8_SA(b, h) + aoff + m * 2048 + k * 1024); } while (0)
; #define PG8_LDB(dst, b, h) do { _Pragma("unroll") for (int n = 0; n < 2; ++n) _Pragma("unroll") for (int k = 0; k < 2; ++k) dst[n][k] = *(const PG8_LAS bf16x8*)(lds + PG8_SB(b, h) + boff + n * 2048 + k * 1024); } while (0)
; #define PG8_MMA_NP(ai, bj, At, Bt) do { _Pragma("unroll") for (int m = 0; m < 4; ++m) _Pragma("unroll") for (int n = 0; n < 2; ++n) _Pragma("unroll") for (int k = 0; k < 2; ++k) \
;         acc[ai][bj][m][n] = __builtin_amdgcn_mfma_f32_16x16x32_bf16(Bt[n][k], At[m][k], acc[ai][bj][m][n], 0, 0, 0); } while (0)
; #define PG8_WAIT_V(n) asm volatile("s_waitcnt vmcnt(" #n ")" ::: "memory")
; #define PG8_WAIT_L(n) asm volatile("s_waitcnt lgkmcnt(" #n ")" ::: "memory")
; #define PG8_BAR __builtin_amdgcn_s_barrier()
; #define PG8_SCHED __builtin_amdgcn_sched_barrier(0)
; template <class Epi, class Sched, bool ALIGN_EPI = false, bool SP2 = false>
; __device__ __forceinline__ void gemm_phase(PG8_LAS unsigned char* lds, const Gemm g, const Sched& S, const Epi& E) {
;     ...
;             PG8_WAIT_V(8); PG8_WAIT_L(0); PG8_BAR; __builtin_amdgcn_s_setprio(1); PG8_MMA_NP(1, 0, At, B0); PG8_MMA_NP(1, 1, At, B1); __builtin_amdgcn_s_setprio(0); PG8_BAR; PG8_SCHED;
;             PG8_LDB(B0, 1, 0); PG8_LDB(B1, 1, 1); PG8_SCHED; PG8_LDA(At, 1, 0); PG8_STAGE(PG8_SA(0, 1), a2 + hstep, voffA);
;             PG8_WAIT_V(8); PG8_WAIT_L(0); PG8_BAR; __builtin_amdgcn_s_setprio(1); PG8_MMA_NP(0, 0, At, B0); PG8_MMA_NP(0, 1, At, B1); __builtin_amdgcn_s_setprio(0); PG8_BAR; PG8_SCHED;
	s_setprio 1
	s_waitcnt lgkmcnt(0)
	v_mfma_f32_16x16x32_bf16 v[62:65], v[130:133], v[206:209], 0
	v_mfma_f32_16x16x32_bf16 v[54:57], v[150:153], v[206:209], 0
	v_mfma_f32_16x16x32_bf16 v[46:49], v[130:133], v[214:217], 0
	v_mfma_f32_16x16x32_bf16 v[38:41], v[150:153], v[214:217], 0
	v_mfma_f32_16x16x32_bf16 v[30:33], v[130:133], v[222:225], 0
	v_mfma_f32_16x16x32_bf16 v[22:25], v[150:153], v[222:225], 0
	v_mfma_f32_16x16x32_bf16 v[14:17], v[130:133], v[230:233], 0
	v_mfma_f32_16x16x32_bf16 v[6:9], v[150:153], v[230:233], 0
	v_mfma_f32_16x16x32_bf16 v[58:61], v[158:161], v[206:209], 0
	v_mfma_f32_16x16x32_bf16 v[50:53], v[186:189], v[206:209], 0
	v_mfma_f32_16x16x32_bf16 v[42:45], v[158:161], v[214:217], 0
	v_mfma_f32_16x16x32_bf16 v[34:37], v[186:189], v[214:217], 0
	v_mfma_f32_16x16x32_bf16 v[26:29], v[158:161], v[222:225], 0
	v_mfma_f32_16x16x32_bf16 v[18:21], v[186:189], v[222:225], 0
	v_mfma_f32_16x16x32_bf16 v[10:13], v[158:161], v[230:233], 0
	v_mfma_f32_16x16x32_bf16 v[2:5], v[186:189], v[230:233], 0
	v_mfma_f32_16x16x32_bf16 v[62:65], v[146:149], v[210:213], v[62:65]
	v_mfma_f32_16x16x32_bf16 v[54:57], v[154:157], v[210:213], v[54:57]
	v_mfma_f32_16x16x32_bf16 v[46:49], v[146:149], v[218:221], v[46:49]
	v_mfma_f32_16x16x32_bf16 v[38:41], v[154:157], v[218:221], v[38:41]
	v_mfma_f32_16x16x32_bf16 v[30:33], v[146:149], v[226:229], v[30:33]
	v_mfma_f32_16x16x32_bf16 v[22:25], v[154:157], v[226:229], v[22:25]
	v_mfma_f32_16x16x32_bf16 v[14:17], v[146:149], v[234:237], v[14:17]
	v_mfma_f32_16x16x32_bf16 v[6:9], v[154:157], v[234:237], v[6:9]
	v_mfma_f32_16x16x32_bf16 v[58:61], v[178:181], v[210:213], v[58:61]
	v_mfma_f32_16x16x32_bf16 v[50:53], v[202:205], v[210:213], v[50:53]
	v_mfma_f32_16x16x32_bf16 v[42:45], v[178:181], v[218:221], v[42:45]
	v_mfma_f32_16x16x32_bf16 v[34:37], v[202:205], v[218:221], v[34:37]
	v_mfma_f32_16x16x32_bf16 v[26:29], v[178:181], v[226:229], v[26:29]
	v_mfma_f32_16x16x32_bf16 v[18:21], v[202:205], v[226:229], v[18:21]
	v_mfma_f32_16x16x32_bf16 v[10:13], v[178:181], v[234:237], v[10:13]
	v_mfma_f32_16x16x32_bf16 v[2:5], v[202:205], v[234:237], v[2:5]
	s_setprio 0
	s_barrier
	s_add_i32 s22, 0, 0x18000
	s_add_i32 s23, 0, 0x1c000
	v_add_u32_e32 v154, s22, v183
	v_add_u32_e32 v202, s23, v183
	ds_read_b128 v[130:133], v154
	ds_read_b128 v[146:149], v154 offset:1024
	ds_read_b128 v[150:153], v154 offset:2048
	ds_read_b128 v[154:157], v154 offset:3072
	ds_read_b128 v[158:161], v202
	ds_read_b128 v[178:181], v202 offset:1024
	ds_read_b128 v[186:189], v202 offset:2048
	ds_read_b128 v[202:205], v202 offset:3072
	s_add_u32 s14, s14, 0x40000
	s_addc_u32 s15, s15, 0
	s_mov_b32 m0, s40
	v_lshl_add_u64 v[242:243], s[14:15], 0, v[138:139]
	ds_read_b128 v[206:209], v185 offset:32768
	ds_read_b128 v[210:213], v185 offset:33792
	ds_read_b128 v[214:217], v185 offset:34816
	ds_read_b128 v[218:221], v185 offset:35840
	ds_read_b128 v[222:225], v185 offset:36864
	ds_read_b128 v[226:229], v185 offset:37888
	ds_read_b128 v[230:233], v185 offset:38912
	ds_read_b128 v[234:237], v185 offset:39936
	global_load_lds_dwordx4 v[242:243], off
	v_lshl_add_u64 v[242:243], s[14:15], 0, v[136:137]
	s_mov_b32 m0, s41
	s_nop 0
	global_load_lds_dwordx4 v[242:243], off
	s_waitcnt vmcnt(8)
	s_waitcnt lgkmcnt(0)
	s_barrier
	s_setprio 1
	s_waitcnt lgkmcnt(0)
	v_mfma_f32_16x16x32_bf16 v[126:129], v[130:133], v[206:209], v[126:129]
	v_mfma_f32_16x16x32_bf16 v[118:121], v[150:153], v[206:209], v[118:121]
	v_mfma_f32_16x16x32_bf16 v[110:113], v[130:133], v[214:217], v[110:113]
	v_mfma_f32_16x16x32_bf16 v[102:105], v[150:153], v[214:217], v[102:105]
	v_mfma_f32_16x16x32_bf16 v[94:97], v[130:133], v[222:225], v[94:97]
	v_mfma_f32_16x16x32_bf16 v[86:89], v[150:153], v[222:225], v[86:89]
	v_mfma_f32_16x16x32_bf16 v[78:81], v[130:133], v[230:233], v[78:81]
	v_mfma_f32_16x16x32_bf16 v[70:73], v[150:153], v[230:233], v[70:73]
	v_mfma_f32_16x16x32_bf16 v[122:125], v[158:161], v[206:209], v[122:125]
	v_mfma_f32_16x16x32_bf16 v[114:117], v[186:189], v[206:209], v[114:117]
	v_mfma_f32_16x16x32_bf16 v[106:109], v[158:161], v[214:217], v[106:109]
	v_mfma_f32_16x16x32_bf16 v[98:101], v[186:189], v[214:217], v[98:101]
	v_mfma_f32_16x16x32_bf16 v[90:93], v[158:161], v[222:225], v[90:93]
	v_mfma_f32_16x16x32_bf16 v[82:85], v[186:189], v[222:225], v[82:85]
	v_mfma_f32_16x16x32_bf16 v[74:77], v[158:161], v[230:233], v[74:77]
	v_mfma_f32_16x16x32_bf16 v[66:69], v[186:189], v[230:233], v[66:69]
	v_mfma_f32_16x16x32_bf16 v[126:129], v[146:149], v[210:213], v[126:129]
	v_mfma_f32_16x16x32_bf16 v[118:121], v[154:157], v[210:213], v[118:121]
	v_mfma_f32_16x16x32_bf16 v[110:113], v[146:149], v[218:221], v[110:113]
	v_mfma_f32_16x16x32_bf16 v[102:105], v[154:157], v[218:221], v[102:105]
	v_mfma_f32_16x16x32_bf16 v[94:97], v[146:149], v[226:229], v[94:97]
	v_mfma_f32_16x16x32_bf16 v[86:89], v[154:157], v[226:229], v[86:89]
	v_mfma_f32_16x16x32_bf16 v[78:81], v[146:149], v[234:237], v[78:81]
	v_mfma_f32_16x16x32_bf16 v[70:73], v[154:157], v[234:237], v[70:73]
	v_mfma_f32_16x16x32_bf16 v[122:125], v[178:181], v[210:213], v[122:125]
	v_mfma_f32_16x16x32_bf16 v[114:117], v[202:205], v[210:213], v[114:117]
	v_mfma_f32_16x16x32_bf16 v[106:109], v[178:181], v[218:221], v[106:109]
	v_mfma_f32_16x16x32_bf16 v[98:101], v[202:205], v[218:221], v[98:101]
	v_mfma_f32_16x16x32_bf16 v[90:93], v[178:181], v[226:229], v[90:93]
	v_mfma_f32_16x16x32_bf16 v[82:85], v[202:205], v[226:229], v[82:85]
	v_mfma_f32_16x16x32_bf16 v[74:77], v[178:181], v[234:237], v[74:77]
	v_mfma_f32_16x16x32_bf16 v[66:69], v[202:205], v[234:237], v[66:69]
	s_setprio 0
	s_barrier
; #define PG8_STAGE(bufoff, gbase, voff) do { _Pragma("unroll") for (int _i = 0; _i < 2; ++_i) \
;         __builtin_amdgcn_global_load_lds((const unsigned*)((const char*)(gbase) + (voff)[_i]), (PG8_LAS unsigned*)(lds + (bufoff) + ldsw + _i * 8192), 16, 0, 0); } while (0)
; #define PG8_LDA(dst, b, h) do { _Pragma("unroll") for (int m = 0; m < 4; ++m) _Pragma("unroll") for (int k = 0; k < 2; ++k) dst[m][k] = *(const PG8_LAS bf16x8*)(lds + PG8_SA(b, h) + aoff + m * 2048 + k * 1024); } while (0)
; #define PG8_MMA_NP(ai, bj, At, Bt) do { _Pragma("unroll") for (int m = 0; m < 4; ++m) _Pragma("unroll") for (int n = 0; n < 2; ++n) _Pragma("unroll") for (int k = 0; k < 2; ++k) \
;         acc[ai][bj][m][n] = __builtin_amdgcn_mfma_f32_16x16x32_bf16(Bt[n][k], At[m][k], acc[ai][bj][m][n], 0, 0, 0); } while (0)
; #define PG8_WAIT_V(n) asm volatile("s_waitcnt vmcnt(" #n ")" ::: "memory")
; #define PG8_WAIT_L(n) asm volatile("s_waitcnt lgkmcnt(" #n ")" ::: "memory")
; #define PG8_BAR __builtin_amdgcn_s_barrier()
; #define PG8_SCHED __builtin_amdgcn_sched_barrier(0)
; template <class Epi, class Sched, bool ALIGN_EPI = false, bool SP2 = false>
; __device__ __forceinline__ void gemm_phase(PG8_LAS unsigned char* lds, const Gemm g, const Sched& S, const Epi& E) {
;     ...
;         for (int t = 0; t < nt; t += 2) {
;     ...
;             PG8_LDA(At, 1, 1); PG8_STAGE(PG8_SB(1, 0), b3, voffB); PG8_STAGE(PG8_SB(1, 1), b3 + hstep, voffB); PG8_STAGE(PG8_SA(1, 0), a3, voffA);
;             PG8_WAIT_V(8); PG8_WAIT_L(0); PG8_BAR; __builtin_amdgcn_s_setprio(1); PG8_MMA_NP(1, 0, At, B0); PG8_MMA_NP(1, 1, At, B1); __builtin_amdgcn_s_setprio(0); PG8_BAR; PG8_SCHED;
	s_add_i32 s14, s22, s29
	v_lshl_add_u64 v[162:163], v[162:163], 0, s[20:21]
	s_mov_b32 m0, s14
	ds_read_b128 v[206:209], v185 offset:49152
	ds_read_b128 v[210:213], v185 offset:50176
	ds_read_b128 v[214:217], v185 offset:51200
	ds_read_b128 v[218:221], v185 offset:52224
	ds_read_b128 v[222:225], v185 offset:53248
	ds_read_b128 v[226:229], v185 offset:54272
	ds_read_b128 v[230:233], v185 offset:55296
	ds_read_b128 v[234:237], v185 offset:56320
	global_load_lds_dwordx4 v[162:163], off
	s_add_i32 m0, s14, 0x2000
	s_add_u32 s12, s12, 0x40080
	v_lshl_add_u64 v[162:163], v[190:191], 0, s[20:21]
	s_addc_u32 s13, s13, 0
	s_add_i32 s14, s23, s29
	global_load_lds_dwordx4 v[162:163], off
	v_lshl_add_u64 v[162:163], s[12:13], 0, v[0:1]
	s_mov_b32 m0, s14
	s_nop 0
	global_load_lds_dwordx4 v[162:163], off
	v_lshl_add_u64 v[162:163], s[12:13], 0, v[134:135]
	s_add_i32 m0, s14, 0x2000
	s_nop 0
	global_load_lds_dwordx4 v[162:163], off
	v_lshl_add_u64 v[162:163], v[238:239], 0, s[20:21]
	s_mov_b32 m0, s54
	s_nop 0
	global_load_lds_dwordx4 v[162:163], off
	v_lshl_add_u64 v[162:163], v[240:241], 0, s[20:21]
	s_mov_b32 m0, s55
	s_nop 0
	global_load_lds_dwordx4 v[162:163], off
	s_waitcnt vmcnt(8)
	s_waitcnt lgkmcnt(0)
	s_barrier
	s_setprio 1
	s_waitcnt lgkmcnt(0)
	v_mfma_f32_16x16x32_bf16 v[62:65], v[130:133], v[206:209], v[62:65]
	v_mfma_f32_16x16x32_bf16 v[54:57], v[150:153], v[206:209], v[54:57]
	v_mfma_f32_16x16x32_bf16 v[46:49], v[130:133], v[214:217], v[46:49]
	v_mfma_f32_16x16x32_bf16 v[38:41], v[150:153], v[214:217], v[38:41]
	v_mfma_f32_16x16x32_bf16 v[30:33], v[130:133], v[222:225], v[30:33]
	v_mfma_f32_16x16x32_bf16 v[22:25], v[150:153], v[222:225], v[22:25]
	v_mfma_f32_16x16x32_bf16 v[14:17], v[130:133], v[230:233], v[14:17]
	v_mfma_f32_16x16x32_bf16 v[6:9], v[150:153], v[230:233], v[6:9]
	v_mfma_f32_16x16x32_bf16 v[58:61], v[158:161], v[206:209], v[58:61]
	v_mfma_f32_16x16x32_bf16 v[50:53], v[186:189], v[206:209], v[50:53]
	v_mfma_f32_16x16x32_bf16 v[42:45], v[158:161], v[214:217], v[42:45]
	v_mfma_f32_16x16x32_bf16 v[34:37], v[186:189], v[214:217], v[34:37]
	v_mfma_f32_16x16x32_bf16 v[26:29], v[158:161], v[222:225], v[26:29]
	v_mfma_f32_16x16x32_bf16 v[18:21], v[186:189], v[222:225], v[18:21]
	v_mfma_f32_16x16x32_bf16 v[10:13], v[158:161], v[230:233], v[10:13]
	v_mfma_f32_16x16x32_bf16 v[2:5], v[186:189], v[230:233], v[2:5]
	v_mfma_f32_16x16x32_bf16 v[62:65], v[146:149], v[210:213], v[62:65]
	v_mfma_f32_16x16x32_bf16 v[54:57], v[154:157], v[210:213], v[54:57]
	v_mfma_f32_16x16x32_bf16 v[46:49], v[146:149], v[218:221], v[46:49]
	v_mfma_f32_16x16x32_bf16 v[38:41], v[154:157], v[218:221], v[38:41]
	v_mfma_f32_16x16x32_bf16 v[30:33], v[146:149], v[226:229], v[30:33]
	v_mfma_f32_16x16x32_bf16 v[22:25], v[154:157], v[226:229], v[22:25]
	v_mfma_f32_16x16x32_bf16 v[14:17], v[146:149], v[234:237], v[14:17]
	v_mfma_f32_16x16x32_bf16 v[6:9], v[154:157], v[234:237], v[6:9]
	v_mfma_f32_16x16x32_bf16 v[58:61], v[178:181], v[210:213], v[58:61]
	v_mfma_f32_16x16x32_bf16 v[50:53], v[202:205], v[210:213], v[50:53]
	v_mfma_f32_16x16x32_bf16 v[42:45], v[178:181], v[218:221], v[42:45]
	v_mfma_f32_16x16x32_bf16 v[34:37], v[202:205], v[218:221], v[34:37]
	v_mfma_f32_16x16x32_bf16 v[26:29], v[178:181], v[226:229], v[26:29]
	v_mfma_f32_16x16x32_bf16 v[18:21], v[202:205], v[226:229], v[18:21]
	v_mfma_f32_16x16x32_bf16 v[10:13], v[178:181], v[234:237], v[10:13]
	v_mfma_f32_16x16x32_bf16 v[2:5], v[202:205], v[234:237], v[2:5]
	s_setprio 0
	s_barrier
	s_add_i32 s63, s63, 2
	s_add_u32 s2, s2, 0x100
	s_addc_u32 s3, s3, 0
	s_add_u32 s61, s61, 0x100
	s_addc_u32 s62, s62, 0
	s_cmp_gt_u32 s63, 13
	s_cbranch_scc0 .LBB0_1122
	s_branch .Lkexit_5
	.p2align 3
	s_nop 0

; template <class Epi, class Sched, bool ALIGN_EPI = false, bool SP2 = false>
; __device__ __forceinline__ void gemm_phase(PG8_LAS unsigned char* lds, const Gemm g, const Sched& S, const Epi& E) {
;     ...
; #pragma unroll
;         for (int a = 0; a < 2; ++a)
; #pragma unroll
;             for (int b = 0; b < 2; ++b)
; #pragma unroll
;                 for (int m = 0; m < 4; ++m)
; #pragma unroll
;                     for (int n = 0; n < 2; ++n) acc[a][b][m][n] = (f32x4){0.f, 0.f, 0.f, 0.f};
.LBB0_1219:
	s_add_u32 s62, s48, 0x100
	v_mov_b32_e32 v2, 0
	s_addc_u32 s63, s49, 0
	s_mov_b32 s64, -2
	s_waitcnt lgkmcnt(0)
	v_mov_b32_e32 v3, v2
	v_mov_b32_e32 v4, v2
	v_mov_b32_e32 v5, v2
	v_mov_b32_e32 v6, v2
	v_mov_b32_e32 v7, v2
	v_mov_b32_e32 v8, v2
	v_mov_b32_e32 v9, v2
	v_mov_b32_e32 v18, v2
	v_mov_b32_e32 v19, v2
	v_mov_b32_e32 v20, v2
	v_mov_b32_e32 v21, v2
	v_mov_b32_e32 v22, v2
	v_mov_b32_e32 v23, v2
	v_mov_b32_e32 v24, v2
	v_mov_b32_e32 v25, v2
	v_mov_b32_e32 v34, v2
	v_mov_b32_e32 v35, v2
	v_mov_b32_e32 v36, v2
	v_mov_b32_e32 v37, v2
	v_mov_b32_e32 v38, v2
	v_mov_b32_e32 v39, v2
	v_mov_b32_e32 v40, v2
	v_mov_b32_e32 v41, v2
	v_mov_b32_e32 v50, v2
	v_mov_b32_e32 v51, v2
	v_mov_b32_e32 v52, v2
	v_mov_b32_e32 v53, v2
	v_mov_b32_e32 v54, v2
	v_mov_b32_e32 v55, v2
	v_mov_b32_e32 v56, v2
	v_mov_b32_e32 v57, v2
	v_mov_b32_e32 v10, v2
	v_mov_b32_e32 v11, v2
	v_mov_b32_e32 v12, v2
	v_mov_b32_e32 v13, v2
	v_mov_b32_e32 v14, v2
	v_mov_b32_e32 v15, v2
	v_mov_b32_e32 v16, v2
	v_mov_b32_e32 v17, v2
	v_mov_b32_e32 v26, v2
	v_mov_b32_e32 v27, v2
	v_mov_b32_e32 v28, v2
	v_mov_b32_e32 v29, v2
	v_mov_b32_e32 v30, v2
	v_mov_b32_e32 v31, v2
	v_mov_b32_e32 v32, v2
	v_mov_b32_e32 v33, v2
	v_mov_b32_e32 v42, v2
	v_mov_b32_e32 v43, v2
	v_mov_b32_e32 v44, v2
	v_mov_b32_e32 v45, v2
	v_mov_b32_e32 v46, v2
	v_mov_b32_e32 v47, v2
	v_mov_b32_e32 v48, v2
	v_mov_b32_e32 v49, v2
	v_mov_b32_e32 v58, v2
	v_mov_b32_e32 v59, v2
	v_mov_b32_e32 v60, v2
	v_mov_b32_e32 v61, v2
	v_mov_b32_e32 v62, v2
	v_mov_b32_e32 v63, v2
	v_mov_b32_e32 v64, v2
	v_mov_b32_e32 v65, v2
	v_mov_b32_e32 v66, v2
	v_mov_b32_e32 v67, v2
	v_mov_b32_e32 v68, v2
	v_mov_b32_e32 v69, v2
	v_mov_b32_e32 v70, v2
	v_mov_b32_e32 v71, v2
	v_mov_b32_e32 v72, v2
	v_mov_b32_e32 v73, v2
	v_mov_b32_e32 v82, v2
	v_mov_b32_e32 v83, v2
	v_mov_b32_e32 v84, v2
	v_mov_b32_e32 v85, v2
	v_mov_b32_e32 v86, v2
	v_mov_b32_e32 v87, v2
	v_mov_b32_e32 v88, v2
	v_mov_b32_e32 v89, v2
	v_mov_b32_e32 v98, v2
	v_mov_b32_e32 v99, v2
	v_mov_b32_e32 v100, v2
	v_mov_b32_e32 v101, v2
	v_mov_b32_e32 v102, v2
	v_mov_b32_e32 v103, v2
	v_mov_b32_e32 v104, v2
	v_mov_b32_e32 v105, v2
	v_mov_b32_e32 v114, v2
	v_mov_b32_e32 v115, v2
	v_mov_b32_e32 v116, v2
	v_mov_b32_e32 v117, v2
	v_mov_b32_e32 v118, v2
	v_mov_b32_e32 v119, v2
	v_mov_b32_e32 v120, v2
	v_mov_b32_e32 v121, v2
	v_mov_b32_e32 v74, v2
	v_mov_b32_e32 v75, v2
	v_mov_b32_e32 v76, v2
	v_mov_b32_e32 v77, v2
	v_mov_b32_e32 v78, v2
	v_mov_b32_e32 v79, v2
	v_mov_b32_e32 v80, v2
	v_mov_b32_e32 v81, v2
	v_mov_b32_e32 v90, v2
	v_mov_b32_e32 v91, v2
	v_mov_b32_e32 v92, v2
	v_mov_b32_e32 v93, v2
	v_mov_b32_e32 v94, v2
	v_mov_b32_e32 v95, v2
	v_mov_b32_e32 v96, v2
	v_mov_b32_e32 v97, v2
	v_mov_b32_e32 v106, v2
	v_mov_b32_e32 v107, v2
	v_mov_b32_e32 v108, v2
	v_mov_b32_e32 v109, v2
	v_mov_b32_e32 v110, v2
	v_mov_b32_e32 v111, v2
	v_mov_b32_e32 v112, v2
	v_mov_b32_e32 v113, v2
	v_mov_b32_e32 v122, v2
	v_mov_b32_e32 v123, v2
	v_mov_b32_e32 v124, v2
	v_mov_b32_e32 v125, v2
	v_mov_b32_e32 v126, v2
	v_mov_b32_e32 v127, v2
	v_mov_b32_e32 v128, v2
	v_mov_b32_e32 v129, v2
	.p2align 3
	s_nop 0
